# MFMA issue order within each 8-group changed to Gray-code operand order (one operand changes per step)
# speedup vs baseline: 1.0112x; 1.0031x over previous
.LBB0_808:
	s_ashr_i32 s21, s20, 31
	s_lshl_b64 s[22:23], s[20:21], 19
	v_readlane_b32 s24, v254, 28
	v_readlane_b32 s25, v254, 29
	s_add_u32 s22, s24, s22
	s_addc_u32 s23, s25, s23
	s_and_b64 s[24:25], s[4:5], exec
	s_cselect_b32 s7, s23, s9
	s_cselect_b32 s21, s22, s8
	s_ashr_i32 s19, s18, 31
	s_lshl_b64 s[24:25], s[18:19], 19
	s_add_u32 s24, s34, s24
	s_addc_u32 s25, s35, s25
	s_and_b64 s[30:31], s[4:5], exec
	s_cselect_b32 s19, s25, s29
	s_cselect_b32 s27, s24, s28
	s_add_u32 s8, s8, 0x40080
	s_addc_u32 s9, s9, 0
	s_add_u32 s53, s28, 0x100
	s_addc_u32 s54, s29, 0
	s_mov_b32 s55, -2
	s_add_u32 s28, s8, 0xfffc0080
	s_addc_u32 s29, s9, -1
	s_add_i32 s56, 0, 0x10000
	s_cmp_eq_u32 s55, 12
	s_cselect_b32 s31, s7, s29
	s_cselect_b32 s30, s21, s28
	s_cselect_b32 s29, s19, s54
	s_cselect_b32 s28, s27, s53
	s_add_i32 s58, 0, 0x14000
	v_add_u32_e32 v142, s56, v224
	v_add_u32_e32 v162, s58, v224
	ds_read_b128 v[130:133], v142
	ds_read_b128 v[134:137], v142 offset:1024
	ds_read_b128 v[138:141], v142 offset:2048
	ds_read_b128 v[142:145], v142 offset:3072
	ds_read_b128 v[146:149], v162
	ds_read_b128 v[150:153], v162 offset:1024
	ds_read_b128 v[176:179], v162 offset:2048
	ds_read_b128 v[180:183], v162 offset:3072
	v_lshl_add_u64 v[162:163], s[8:9], 0, v[172:173]
	s_add_i32 m0, s37, 0xc000
	ds_read_b128 v[184:187], v226
	ds_read_b128 v[188:191], v226 offset:1024
	ds_read_b128 v[192:195], v226 offset:2048
	ds_read_b128 v[196:199], v226 offset:3072
	ds_read_b128 v[200:203], v226 offset:4096
	ds_read_b128 v[204:207], v226 offset:5120
	ds_read_b128 v[228:231], v226 offset:6144
	ds_read_b128 v[232:235], v226 offset:7168
	global_load_lds_dwordx4 v[162:163], off
	v_lshl_add_u64 v[162:163], s[8:9], 0, v[174:175]
	s_add_i32 m0, s37, 0xe000
	s_nop 0
	global_load_lds_dwordx4 v[162:163], off
	s_waitcnt vmcnt(16)
	s_waitcnt lgkmcnt(0)
	s_barrier
	s_setprio 1
	s_waitcnt lgkmcnt(0)
	v_mfma_f32_16x16x32_bf16 v[126:129], v[130:133], v[184:187], 0
	v_mfma_f32_16x16x32_bf16 v[122:125], v[138:141], v[184:187], 0
	v_mfma_f32_16x16x32_bf16 v[106:109], v[138:141], v[192:195], 0
	v_mfma_f32_16x16x32_bf16 v[110:113], v[130:133], v[192:195], 0
	v_mfma_f32_16x16x32_bf16 v[94:97], v[130:133], v[200:203], 0
	v_mfma_f32_16x16x32_bf16 v[90:93], v[138:141], v[200:203], 0
	v_mfma_f32_16x16x32_bf16 v[74:77], v[138:141], v[228:231], 0
	v_mfma_f32_16x16x32_bf16 v[78:81], v[130:133], v[228:231], 0
	v_mfma_f32_16x16x32_bf16 v[126:129], v[134:137], v[188:191], v[126:129]
	v_mfma_f32_16x16x32_bf16 v[122:125], v[142:145], v[188:191], v[122:125]
	v_mfma_f32_16x16x32_bf16 v[106:109], v[142:145], v[196:199], v[106:109]
	v_mfma_f32_16x16x32_bf16 v[110:113], v[134:137], v[196:199], v[110:113]
	v_mfma_f32_16x16x32_bf16 v[94:97], v[134:137], v[204:207], v[94:97]
	v_mfma_f32_16x16x32_bf16 v[90:93], v[142:145], v[204:207], v[90:93]
	v_mfma_f32_16x16x32_bf16 v[74:77], v[142:145], v[232:235], v[74:77]
	v_mfma_f32_16x16x32_bf16 v[78:81], v[134:137], v[232:235], v[78:81]
	s_setprio 0
	s_setprio 1
	v_mfma_f32_16x16x32_bf16 v[118:121], v[146:149], v[184:187], 0
	v_mfma_f32_16x16x32_bf16 v[114:117], v[176:179], v[184:187], 0
	v_mfma_f32_16x16x32_bf16 v[98:101], v[176:179], v[192:195], 0
	v_mfma_f32_16x16x32_bf16 v[102:105], v[146:149], v[192:195], 0
	v_mfma_f32_16x16x32_bf16 v[86:89], v[146:149], v[200:203], 0
	v_mfma_f32_16x16x32_bf16 v[82:85], v[176:179], v[200:203], 0
	v_mfma_f32_16x16x32_bf16 v[66:69], v[176:179], v[228:231], 0
	v_mfma_f32_16x16x32_bf16 v[70:73], v[146:149], v[228:231], 0
	v_mfma_f32_16x16x32_bf16 v[118:121], v[150:153], v[188:191], v[118:121]
	v_mfma_f32_16x16x32_bf16 v[114:117], v[180:183], v[188:191], v[114:117]
	v_mfma_f32_16x16x32_bf16 v[98:101], v[180:183], v[196:199], v[98:101]
	v_mfma_f32_16x16x32_bf16 v[102:105], v[150:153], v[196:199], v[102:105]
	v_mfma_f32_16x16x32_bf16 v[86:89], v[150:153], v[204:207], v[86:89]
	v_mfma_f32_16x16x32_bf16 v[82:85], v[180:183], v[204:207], v[82:85]
	v_mfma_f32_16x16x32_bf16 v[66:69], v[180:183], v[232:235], v[66:69]
	v_mfma_f32_16x16x32_bf16 v[70:73], v[150:153], v[232:235], v[70:73]
	s_setprio 0
	s_barrier
	s_add_i32 s56, s56, s36
	v_lshl_add_u64 v[162:163], s[28:29], 0, v[0:1]
	s_mov_b32 m0, s56
	ds_read_b128 v[184:187], v226 offset:16384
	ds_read_b128 v[188:191], v226 offset:17408
	ds_read_b128 v[192:195], v226 offset:18432
	ds_read_b128 v[196:199], v226 offset:19456
	ds_read_b128 v[200:203], v226 offset:20480
	ds_read_b128 v[204:207], v226 offset:21504
	ds_read_b128 v[228:231], v226 offset:22528
	ds_read_b128 v[232:235], v226 offset:23552
	global_load_lds_dwordx4 v[162:163], off
	s_add_i32 m0, s56, 0x2000
	s_add_u32 s56, s28, 0x40000
	v_lshl_add_u64 v[208:209], s[28:29], 0, v[158:159]
	s_addc_u32 s57, s29, 0
	s_add_i32 s58, s58, s36
	global_load_lds_dwordx4 v[208:209], off
	v_lshl_add_u64 v[214:215], s[56:57], 0, v[0:1]
	s_mov_b32 m0, s58
	v_lshl_add_u64 v[216:217], s[30:31], 0, v[156:157]
	global_load_lds_dwordx4 v[214:215], off
	v_lshl_add_u64 v[214:215], s[56:57], 0, v[158:159]
	s_add_i32 m0, s58, 0x2000
	s_nop 0
	global_load_lds_dwordx4 v[214:215], off
	v_lshl_add_u64 v[214:215], s[30:31], 0, v[154:155]
	s_mov_b32 m0, s37
	s_nop 0
	global_load_lds_dwordx4 v[214:215], off
	s_mov_b32 m0, s38
	s_nop 0
	global_load_lds_dwordx4 v[216:217], off
	s_cmp_eq_u32 s46, 1
	s_cbranch_scc1 .Lpj_peel_w8
	s_waitcnt vmcnt(16)
	s_branch .Lpj_peel_wj

.Lpj_peel_wj:
	s_waitcnt lgkmcnt(0)
	s_barrier
	s_setprio 1
	s_waitcnt lgkmcnt(0)
	v_mfma_f32_16x16x32_bf16 v[62:65], v[130:133], v[184:187], 0
	v_mfma_f32_16x16x32_bf16 v[58:61], v[138:141], v[184:187], 0
	v_mfma_f32_16x16x32_bf16 v[42:45], v[138:141], v[192:195], 0
	v_mfma_f32_16x16x32_bf16 v[46:49], v[130:133], v[192:195], 0
	v_mfma_f32_16x16x32_bf16 v[30:33], v[130:133], v[200:203], 0
	v_mfma_f32_16x16x32_bf16 v[26:29], v[138:141], v[200:203], 0
	v_mfma_f32_16x16x32_bf16 v[10:13], v[138:141], v[228:231], 0
	v_mfma_f32_16x16x32_bf16 v[14:17], v[130:133], v[228:231], 0
	v_mfma_f32_16x16x32_bf16 v[62:65], v[134:137], v[188:191], v[62:65]
	v_mfma_f32_16x16x32_bf16 v[58:61], v[142:145], v[188:191], v[58:61]
	v_mfma_f32_16x16x32_bf16 v[42:45], v[142:145], v[196:199], v[42:45]
	v_mfma_f32_16x16x32_bf16 v[46:49], v[134:137], v[196:199], v[46:49]
	v_mfma_f32_16x16x32_bf16 v[30:33], v[134:137], v[204:207], v[30:33]
	v_mfma_f32_16x16x32_bf16 v[26:29], v[142:145], v[204:207], v[26:29]
	v_mfma_f32_16x16x32_bf16 v[10:13], v[142:145], v[232:235], v[10:13]
	v_mfma_f32_16x16x32_bf16 v[14:17], v[134:137], v[232:235], v[14:17]
	s_setprio 0
	s_setprio 1
	v_mfma_f32_16x16x32_bf16 v[54:57], v[146:149], v[184:187], 0
	v_mfma_f32_16x16x32_bf16 v[50:53], v[176:179], v[184:187], 0
	v_mfma_f32_16x16x32_bf16 v[34:37], v[176:179], v[192:195], 0
	v_mfma_f32_16x16x32_bf16 v[38:41], v[146:149], v[192:195], 0
	v_mfma_f32_16x16x32_bf16 v[22:25], v[146:149], v[200:203], 0
	v_mfma_f32_16x16x32_bf16 v[18:21], v[176:179], v[200:203], 0
	v_mfma_f32_16x16x32_bf16 v[2:5], v[176:179], v[228:231], 0
	v_mfma_f32_16x16x32_bf16 v[6:9], v[146:149], v[228:231], 0
	v_mfma_f32_16x16x32_bf16 v[54:57], v[150:153], v[188:191], v[54:57]
	v_mfma_f32_16x16x32_bf16 v[50:53], v[180:183], v[188:191], v[50:53]
	v_mfma_f32_16x16x32_bf16 v[34:37], v[180:183], v[196:199], v[34:37]
	v_mfma_f32_16x16x32_bf16 v[38:41], v[150:153], v[196:199], v[38:41]
	v_mfma_f32_16x16x32_bf16 v[22:25], v[150:153], v[204:207], v[22:25]
	v_mfma_f32_16x16x32_bf16 v[18:21], v[180:183], v[204:207], v[18:21]
	v_mfma_f32_16x16x32_bf16 v[2:5], v[180:183], v[232:235], v[2:5]
	v_mfma_f32_16x16x32_bf16 v[6:9], v[150:153], v[232:235], v[6:9]
	s_setprio 0
	s_barrier
	s_add_i32 s56, 0, 0x18000
	s_add_i32 s57, 0, 0x1c000
	v_add_u32_e32 v142, s56, v224
	v_add_u32_e32 v164, s57, v224
	ds_read_b128 v[130:133], v142
	ds_read_b128 v[134:137], v142 offset:1024
	ds_read_b128 v[138:141], v142 offset:2048
	ds_read_b128 v[142:145], v142 offset:3072
	ds_read_b128 v[146:149], v164
	ds_read_b128 v[150:153], v164 offset:1024
	ds_read_b128 v[176:179], v164 offset:2048
	ds_read_b128 v[180:183], v164 offset:3072
	s_add_u32 s30, s30, 0x40000
	s_addc_u32 s31, s31, 0
	s_mov_b32 m0, s39
	v_lshl_add_u64 v[236:237], s[30:31], 0, v[154:155]
	ds_read_b128 v[184:187], v226 offset:32768
	ds_read_b128 v[188:191], v226 offset:33792
	ds_read_b128 v[192:195], v226 offset:34816
	ds_read_b128 v[196:199], v226 offset:35840
	ds_read_b128 v[200:203], v226 offset:36864
	ds_read_b128 v[204:207], v226 offset:37888
	ds_read_b128 v[228:231], v226 offset:38912
	ds_read_b128 v[232:235], v226 offset:39936
	global_load_lds_dwordx4 v[236:237], off
	v_lshl_add_u64 v[236:237], s[30:31], 0, v[156:157]
	s_mov_b32 m0, s40
	s_nop 0
	global_load_lds_dwordx4 v[236:237], off
	s_waitcnt vmcnt(8)
	s_waitcnt lgkmcnt(0)
	s_barrier
	s_setprio 1
	s_waitcnt lgkmcnt(0)
	v_mfma_f32_16x16x32_bf16 v[126:129], v[130:133], v[184:187], v[126:129]
	v_mfma_f32_16x16x32_bf16 v[122:125], v[138:141], v[184:187], v[122:125]
	v_mfma_f32_16x16x32_bf16 v[106:109], v[138:141], v[192:195], v[106:109]
	v_mfma_f32_16x16x32_bf16 v[110:113], v[130:133], v[192:195], v[110:113]
	v_mfma_f32_16x16x32_bf16 v[94:97], v[130:133], v[200:203], v[94:97]
	v_mfma_f32_16x16x32_bf16 v[90:93], v[138:141], v[200:203], v[90:93]
	v_mfma_f32_16x16x32_bf16 v[74:77], v[138:141], v[228:231], v[74:77]
	v_mfma_f32_16x16x32_bf16 v[78:81], v[130:133], v[228:231], v[78:81]
	v_mfma_f32_16x16x32_bf16 v[126:129], v[134:137], v[188:191], v[126:129]
	v_mfma_f32_16x16x32_bf16 v[122:125], v[142:145], v[188:191], v[122:125]
	v_mfma_f32_16x16x32_bf16 v[106:109], v[142:145], v[196:199], v[106:109]
	v_mfma_f32_16x16x32_bf16 v[110:113], v[134:137], v[196:199], v[110:113]
	v_mfma_f32_16x16x32_bf16 v[94:97], v[134:137], v[204:207], v[94:97]
	v_mfma_f32_16x16x32_bf16 v[90:93], v[142:145], v[204:207], v[90:93]
	v_mfma_f32_16x16x32_bf16 v[74:77], v[142:145], v[232:235], v[74:77]
	v_mfma_f32_16x16x32_bf16 v[78:81], v[134:137], v[232:235], v[78:81]
	s_setprio 0
	s_setprio 1
	v_mfma_f32_16x16x32_bf16 v[118:121], v[146:149], v[184:187], v[118:121]
	v_mfma_f32_16x16x32_bf16 v[114:117], v[176:179], v[184:187], v[114:117]
	v_mfma_f32_16x16x32_bf16 v[98:101], v[176:179], v[192:195], v[98:101]
	v_mfma_f32_16x16x32_bf16 v[102:105], v[146:149], v[192:195], v[102:105]
	v_mfma_f32_16x16x32_bf16 v[86:89], v[146:149], v[200:203], v[86:89]
	v_mfma_f32_16x16x32_bf16 v[82:85], v[176:179], v[200:203], v[82:85]
	v_mfma_f32_16x16x32_bf16 v[66:69], v[176:179], v[228:231], v[66:69]
	v_mfma_f32_16x16x32_bf16 v[70:73], v[146:149], v[228:231], v[70:73]
	v_mfma_f32_16x16x32_bf16 v[118:121], v[150:153], v[188:191], v[118:121]
	v_mfma_f32_16x16x32_bf16 v[114:117], v[180:183], v[188:191], v[114:117]
	v_mfma_f32_16x16x32_bf16 v[98:101], v[180:183], v[196:199], v[98:101]
	v_mfma_f32_16x16x32_bf16 v[102:105], v[150:153], v[196:199], v[102:105]
	v_mfma_f32_16x16x32_bf16 v[86:89], v[150:153], v[204:207], v[86:89]
	v_mfma_f32_16x16x32_bf16 v[82:85], v[180:183], v[204:207], v[82:85]
	v_mfma_f32_16x16x32_bf16 v[66:69], v[180:183], v[232:235], v[66:69]
	v_mfma_f32_16x16x32_bf16 v[70:73], v[150:153], v[232:235], v[70:73]
	s_setprio 0
	s_barrier
	s_add_i32 s30, s56, s36
	v_lshl_add_u64 v[162:163], v[162:163], 0, s[86:87]
	s_mov_b32 m0, s30
	ds_read_b128 v[184:187], v226 offset:49152
	ds_read_b128 v[188:191], v226 offset:50176
	ds_read_b128 v[192:195], v226 offset:51200
	ds_read_b128 v[196:199], v226 offset:52224
	ds_read_b128 v[200:203], v226 offset:53248
	ds_read_b128 v[204:207], v226 offset:54272
	ds_read_b128 v[228:231], v226 offset:55296
	ds_read_b128 v[232:235], v226 offset:56320
	global_load_lds_dwordx4 v[162:163], off
	s_add_i32 m0, s30, 0x2000
	s_add_u32 s28, s28, 0x40080
	v_lshl_add_u64 v[162:163], v[208:209], 0, s[86:87]
	s_addc_u32 s29, s29, 0
	s_add_i32 s30, s57, s36
	global_load_lds_dwordx4 v[162:163], off
	v_lshl_add_u64 v[162:163], s[28:29], 0, v[0:1]
	s_mov_b32 m0, s30
	s_nop 0
	global_load_lds_dwordx4 v[162:163], off
	v_lshl_add_u64 v[162:163], s[28:29], 0, v[158:159]
	s_add_i32 m0, s30, 0x2000
	s_nop 0
	global_load_lds_dwordx4 v[162:163], off
	v_lshl_add_u64 v[162:163], v[214:215], 0, s[86:87]
	s_mov_b32 m0, s44
	s_nop 0
	global_load_lds_dwordx4 v[162:163], off
	v_lshl_add_u64 v[162:163], v[216:217], 0, s[86:87]
	s_mov_b32 m0, s45
	s_nop 0
	global_load_lds_dwordx4 v[162:163], off
	s_waitcnt vmcnt(8)
	s_waitcnt lgkmcnt(0)
	s_barrier
	s_setprio 1
	s_waitcnt lgkmcnt(0)
	v_mfma_f32_16x16x32_bf16 v[62:65], v[130:133], v[184:187], v[62:65]
	v_mfma_f32_16x16x32_bf16 v[58:61], v[138:141], v[184:187], v[58:61]
	v_mfma_f32_16x16x32_bf16 v[42:45], v[138:141], v[192:195], v[42:45]
	v_mfma_f32_16x16x32_bf16 v[46:49], v[130:133], v[192:195], v[46:49]
	v_mfma_f32_16x16x32_bf16 v[30:33], v[130:133], v[200:203], v[30:33]
	v_mfma_f32_16x16x32_bf16 v[26:29], v[138:141], v[200:203], v[26:29]
	v_mfma_f32_16x16x32_bf16 v[10:13], v[138:141], v[228:231], v[10:13]
	v_mfma_f32_16x16x32_bf16 v[14:17], v[130:133], v[228:231], v[14:17]
	v_mfma_f32_16x16x32_bf16 v[62:65], v[134:137], v[188:191], v[62:65]
	v_mfma_f32_16x16x32_bf16 v[58:61], v[142:145], v[188:191], v[58:61]
	v_mfma_f32_16x16x32_bf16 v[42:45], v[142:145], v[196:199], v[42:45]
	v_mfma_f32_16x16x32_bf16 v[46:49], v[134:137], v[196:199], v[46:49]
	v_mfma_f32_16x16x32_bf16 v[30:33], v[134:137], v[204:207], v[30:33]
	v_mfma_f32_16x16x32_bf16 v[26:29], v[142:145], v[204:207], v[26:29]
	v_mfma_f32_16x16x32_bf16 v[10:13], v[142:145], v[232:235], v[10:13]
	v_mfma_f32_16x16x32_bf16 v[14:17], v[134:137], v[232:235], v[14:17]
	s_setprio 0
	s_setprio 1
	v_mfma_f32_16x16x32_bf16 v[54:57], v[146:149], v[184:187], v[54:57]
	v_mfma_f32_16x16x32_bf16 v[50:53], v[176:179], v[184:187], v[50:53]
	v_mfma_f32_16x16x32_bf16 v[34:37], v[176:179], v[192:195], v[34:37]
	v_mfma_f32_16x16x32_bf16 v[38:41], v[146:149], v[192:195], v[38:41]
	v_mfma_f32_16x16x32_bf16 v[22:25], v[146:149], v[200:203], v[22:25]
	v_mfma_f32_16x16x32_bf16 v[18:21], v[176:179], v[200:203], v[18:21]
	v_mfma_f32_16x16x32_bf16 v[2:5], v[176:179], v[228:231], v[2:5]
	v_mfma_f32_16x16x32_bf16 v[6:9], v[146:149], v[228:231], v[6:9]
	v_mfma_f32_16x16x32_bf16 v[54:57], v[150:153], v[188:191], v[54:57]
	v_mfma_f32_16x16x32_bf16 v[50:53], v[180:183], v[188:191], v[50:53]
	v_mfma_f32_16x16x32_bf16 v[34:37], v[180:183], v[196:199], v[34:37]
	v_mfma_f32_16x16x32_bf16 v[38:41], v[150:153], v[196:199], v[38:41]
	v_mfma_f32_16x16x32_bf16 v[22:25], v[150:153], v[204:207], v[22:25]
	v_mfma_f32_16x16x32_bf16 v[18:21], v[180:183], v[204:207], v[18:21]
	v_mfma_f32_16x16x32_bf16 v[2:5], v[180:183], v[232:235], v[2:5]
	v_mfma_f32_16x16x32_bf16 v[6:9], v[150:153], v[232:235], v[6:9]
	s_setprio 0
	s_barrier
	s_add_i32 s55, s55, 2
	s_add_u32 s8, s8, 0x100
	s_addc_u32 s9, s9, 0
	s_add_u32 s53, s53, 0x100
	s_addc_u32 s54, s54, 0
	s_cmp_gt_u32 s55, 13
	s_cbranch_scc0 .LBB0_809
.LBB0_809:
	s_add_u32 s28, s8, 0xfffc0080
	s_addc_u32 s29, s9, -1
	s_add_i32 s56, 0, 0x10000
	s_cmp_eq_u32 s55, 12
	s_cselect_b32 s31, s7, s29
	s_cselect_b32 s30, s21, s28
	s_cselect_b32 s29, s19, s54
	s_cselect_b32 s28, s27, s53
	s_add_i32 s58, 0, 0x14000
	v_add_u32_e32 v142, s56, v224
	v_add_u32_e32 v162, s58, v224
	ds_read_b128 v[130:133], v142
	ds_read_b128 v[134:137], v142 offset:1024
	ds_read_b128 v[138:141], v142 offset:2048
	ds_read_b128 v[142:145], v142 offset:3072
	ds_read_b128 v[146:149], v162
	ds_read_b128 v[150:153], v162 offset:1024
	ds_read_b128 v[176:179], v162 offset:2048
	ds_read_b128 v[180:183], v162 offset:3072
	v_lshl_add_u64 v[162:163], s[8:9], 0, v[172:173]
	s_add_i32 m0, s37, 0xc000
	ds_read_b128 v[184:187], v226
	ds_read_b128 v[188:191], v226 offset:1024
	ds_read_b128 v[192:195], v226 offset:2048
	ds_read_b128 v[196:199], v226 offset:3072
	ds_read_b128 v[200:203], v226 offset:4096
	ds_read_b128 v[204:207], v226 offset:5120
	ds_read_b128 v[228:231], v226 offset:6144
	ds_read_b128 v[232:235], v226 offset:7168
	global_load_lds_dwordx4 v[162:163], off
	v_lshl_add_u64 v[162:163], s[8:9], 0, v[174:175]
	s_add_i32 m0, s37, 0xe000
	s_nop 0
	global_load_lds_dwordx4 v[162:163], off
	s_waitcnt vmcnt(8)
	s_waitcnt lgkmcnt(0)
	s_barrier
	s_setprio 1
	s_waitcnt lgkmcnt(0)
	v_mfma_f32_16x16x32_bf16 v[126:129], v[130:133], v[184:187], v[126:129]
	v_mfma_f32_16x16x32_bf16 v[122:125], v[138:141], v[184:187], v[122:125]
	v_mfma_f32_16x16x32_bf16 v[106:109], v[138:141], v[192:195], v[106:109]
	v_mfma_f32_16x16x32_bf16 v[110:113], v[130:133], v[192:195], v[110:113]
	v_mfma_f32_16x16x32_bf16 v[94:97], v[130:133], v[200:203], v[94:97]
	v_mfma_f32_16x16x32_bf16 v[90:93], v[138:141], v[200:203], v[90:93]
	v_mfma_f32_16x16x32_bf16 v[74:77], v[138:141], v[228:231], v[74:77]
	v_mfma_f32_16x16x32_bf16 v[78:81], v[130:133], v[228:231], v[78:81]
	v_mfma_f32_16x16x32_bf16 v[126:129], v[134:137], v[188:191], v[126:129]
	v_mfma_f32_16x16x32_bf16 v[122:125], v[142:145], v[188:191], v[122:125]
	v_mfma_f32_16x16x32_bf16 v[106:109], v[142:145], v[196:199], v[106:109]
	v_mfma_f32_16x16x32_bf16 v[110:113], v[134:137], v[196:199], v[110:113]
	v_mfma_f32_16x16x32_bf16 v[94:97], v[134:137], v[204:207], v[94:97]
	v_mfma_f32_16x16x32_bf16 v[90:93], v[142:145], v[204:207], v[90:93]
	v_mfma_f32_16x16x32_bf16 v[74:77], v[142:145], v[232:235], v[74:77]
	v_mfma_f32_16x16x32_bf16 v[78:81], v[134:137], v[232:235], v[78:81]
	s_setprio 0
	s_setprio 1
	v_mfma_f32_16x16x32_bf16 v[118:121], v[146:149], v[184:187], v[118:121]
	v_mfma_f32_16x16x32_bf16 v[114:117], v[176:179], v[184:187], v[114:117]
	v_mfma_f32_16x16x32_bf16 v[98:101], v[176:179], v[192:195], v[98:101]
	v_mfma_f32_16x16x32_bf16 v[102:105], v[146:149], v[192:195], v[102:105]
	v_mfma_f32_16x16x32_bf16 v[86:89], v[146:149], v[200:203], v[86:89]
	v_mfma_f32_16x16x32_bf16 v[82:85], v[176:179], v[200:203], v[82:85]
	v_mfma_f32_16x16x32_bf16 v[66:69], v[176:179], v[228:231], v[66:69]
	v_mfma_f32_16x16x32_bf16 v[70:73], v[146:149], v[228:231], v[70:73]
	v_mfma_f32_16x16x32_bf16 v[118:121], v[150:153], v[188:191], v[118:121]
	v_mfma_f32_16x16x32_bf16 v[114:117], v[180:183], v[188:191], v[114:117]
	v_mfma_f32_16x16x32_bf16 v[98:101], v[180:183], v[196:199], v[98:101]
	v_mfma_f32_16x16x32_bf16 v[102:105], v[150:153], v[196:199], v[102:105]
	v_mfma_f32_16x16x32_bf16 v[86:89], v[150:153], v[204:207], v[86:89]
	v_mfma_f32_16x16x32_bf16 v[82:85], v[180:183], v[204:207], v[82:85]
	v_mfma_f32_16x16x32_bf16 v[66:69], v[180:183], v[232:235], v[66:69]
	v_mfma_f32_16x16x32_bf16 v[70:73], v[150:153], v[232:235], v[70:73]
	s_setprio 0
	s_barrier
	s_add_i32 s56, s56, s36
	v_lshl_add_u64 v[162:163], s[28:29], 0, v[0:1]
	s_mov_b32 m0, s56
	ds_read_b128 v[184:187], v226 offset:16384
	ds_read_b128 v[188:191], v226 offset:17408
	ds_read_b128 v[192:195], v226 offset:18432
	ds_read_b128 v[196:199], v226 offset:19456
	ds_read_b128 v[200:203], v226 offset:20480
	ds_read_b128 v[204:207], v226 offset:21504
	ds_read_b128 v[228:231], v226 offset:22528
	ds_read_b128 v[232:235], v226 offset:23552
	global_load_lds_dwordx4 v[162:163], off
	s_add_i32 m0, s56, 0x2000
	s_add_u32 s56, s28, 0x40000
	v_lshl_add_u64 v[208:209], s[28:29], 0, v[158:159]
	s_addc_u32 s57, s29, 0
	s_add_i32 s58, s58, s36
	global_load_lds_dwordx4 v[208:209], off
	v_lshl_add_u64 v[214:215], s[56:57], 0, v[0:1]
	s_mov_b32 m0, s58
	v_lshl_add_u64 v[216:217], s[30:31], 0, v[156:157]
	global_load_lds_dwordx4 v[214:215], off
	v_lshl_add_u64 v[214:215], s[56:57], 0, v[158:159]
	s_add_i32 m0, s58, 0x2000
	s_nop 0
	global_load_lds_dwordx4 v[214:215], off
	v_lshl_add_u64 v[214:215], s[30:31], 0, v[154:155]
	s_mov_b32 m0, s37
	s_nop 0
	global_load_lds_dwordx4 v[214:215], off
	s_mov_b32 m0, s38
	s_nop 0
	global_load_lds_dwordx4 v[216:217], off
	s_waitcnt vmcnt(8)
	s_waitcnt lgkmcnt(0)
	s_barrier
	s_setprio 1
	s_waitcnt lgkmcnt(0)
	v_mfma_f32_16x16x32_bf16 v[62:65], v[130:133], v[184:187], v[62:65]
	v_mfma_f32_16x16x32_bf16 v[58:61], v[138:141], v[184:187], v[58:61]
	v_mfma_f32_16x16x32_bf16 v[42:45], v[138:141], v[192:195], v[42:45]
	v_mfma_f32_16x16x32_bf16 v[46:49], v[130:133], v[192:195], v[46:49]
	v_mfma_f32_16x16x32_bf16 v[30:33], v[130:133], v[200:203], v[30:33]
	v_mfma_f32_16x16x32_bf16 v[26:29], v[138:141], v[200:203], v[26:29]
	v_mfma_f32_16x16x32_bf16 v[10:13], v[138:141], v[228:231], v[10:13]
	v_mfma_f32_16x16x32_bf16 v[14:17], v[130:133], v[228:231], v[14:17]
	v_mfma_f32_16x16x32_bf16 v[62:65], v[134:137], v[188:191], v[62:65]
	v_mfma_f32_16x16x32_bf16 v[58:61], v[142:145], v[188:191], v[58:61]
	v_mfma_f32_16x16x32_bf16 v[42:45], v[142:145], v[196:199], v[42:45]
	v_mfma_f32_16x16x32_bf16 v[46:49], v[134:137], v[196:199], v[46:49]
	v_mfma_f32_16x16x32_bf16 v[30:33], v[134:137], v[204:207], v[30:33]
	v_mfma_f32_16x16x32_bf16 v[26:29], v[142:145], v[204:207], v[26:29]
	v_mfma_f32_16x16x32_bf16 v[10:13], v[142:145], v[232:235], v[10:13]
	v_mfma_f32_16x16x32_bf16 v[14:17], v[134:137], v[232:235], v[14:17]
	s_setprio 0
	s_setprio 1
	v_mfma_f32_16x16x32_bf16 v[54:57], v[146:149], v[184:187], v[54:57]
	v_mfma_f32_16x16x32_bf16 v[50:53], v[176:179], v[184:187], v[50:53]
	v_mfma_f32_16x16x32_bf16 v[34:37], v[176:179], v[192:195], v[34:37]
	v_mfma_f32_16x16x32_bf16 v[38:41], v[146:149], v[192:195], v[38:41]
	v_mfma_f32_16x16x32_bf16 v[22:25], v[146:149], v[200:203], v[22:25]
	v_mfma_f32_16x16x32_bf16 v[18:21], v[176:179], v[200:203], v[18:21]
	v_mfma_f32_16x16x32_bf16 v[2:5], v[176:179], v[228:231], v[2:5]
	v_mfma_f32_16x16x32_bf16 v[6:9], v[146:149], v[228:231], v[6:9]
	v_mfma_f32_16x16x32_bf16 v[54:57], v[150:153], v[188:191], v[54:57]
	v_mfma_f32_16x16x32_bf16 v[50:53], v[180:183], v[188:191], v[50:53]
	v_mfma_f32_16x16x32_bf16 v[34:37], v[180:183], v[196:199], v[34:37]
	v_mfma_f32_16x16x32_bf16 v[38:41], v[150:153], v[196:199], v[38:41]
	v_mfma_f32_16x16x32_bf16 v[22:25], v[150:153], v[204:207], v[22:25]
	v_mfma_f32_16x16x32_bf16 v[18:21], v[180:183], v[204:207], v[18:21]
	v_mfma_f32_16x16x32_bf16 v[2:5], v[180:183], v[232:235], v[2:5]
	v_mfma_f32_16x16x32_bf16 v[6:9], v[150:153], v[232:235], v[6:9]
	s_setprio 0
	s_barrier
	s_add_i32 s56, 0, 0x18000
	s_add_i32 s57, 0, 0x1c000
	v_add_u32_e32 v142, s56, v224
	v_add_u32_e32 v164, s57, v224
	ds_read_b128 v[130:133], v142
	ds_read_b128 v[134:137], v142 offset:1024
	ds_read_b128 v[138:141], v142 offset:2048
	ds_read_b128 v[142:145], v142 offset:3072
	ds_read_b128 v[146:149], v164
	ds_read_b128 v[150:153], v164 offset:1024
	ds_read_b128 v[176:179], v164 offset:2048
	ds_read_b128 v[180:183], v164 offset:3072
	s_add_u32 s30, s30, 0x40000
	s_addc_u32 s31, s31, 0
	s_mov_b32 m0, s39
	v_lshl_add_u64 v[236:237], s[30:31], 0, v[154:155]
	ds_read_b128 v[184:187], v226 offset:32768
	ds_read_b128 v[188:191], v226 offset:33792
	ds_read_b128 v[192:195], v226 offset:34816
	ds_read_b128 v[196:199], v226 offset:35840
	ds_read_b128 v[200:203], v226 offset:36864
	ds_read_b128 v[204:207], v226 offset:37888
	ds_read_b128 v[228:231], v226 offset:38912
	ds_read_b128 v[232:235], v226 offset:39936
	global_load_lds_dwordx4 v[236:237], off
	v_lshl_add_u64 v[236:237], s[30:31], 0, v[156:157]
	s_mov_b32 m0, s40
	s_nop 0
	global_load_lds_dwordx4 v[236:237], off
	s_waitcnt vmcnt(8)
	s_waitcnt lgkmcnt(0)
	s_barrier
	s_setprio 1
	s_waitcnt lgkmcnt(0)
	v_mfma_f32_16x16x32_bf16 v[126:129], v[130:133], v[184:187], v[126:129]
	v_mfma_f32_16x16x32_bf16 v[122:125], v[138:141], v[184:187], v[122:125]
	v_mfma_f32_16x16x32_bf16 v[106:109], v[138:141], v[192:195], v[106:109]
	v_mfma_f32_16x16x32_bf16 v[110:113], v[130:133], v[192:195], v[110:113]
	v_mfma_f32_16x16x32_bf16 v[94:97], v[130:133], v[200:203], v[94:97]
	v_mfma_f32_16x16x32_bf16 v[90:93], v[138:141], v[200:203], v[90:93]
	v_mfma_f32_16x16x32_bf16 v[74:77], v[138:141], v[228:231], v[74:77]
	v_mfma_f32_16x16x32_bf16 v[78:81], v[130:133], v[228:231], v[78:81]
	v_mfma_f32_16x16x32_bf16 v[126:129], v[134:137], v[188:191], v[126:129]
	v_mfma_f32_16x16x32_bf16 v[122:125], v[142:145], v[188:191], v[122:125]
	v_mfma_f32_16x16x32_bf16 v[106:109], v[142:145], v[196:199], v[106:109]
	v_mfma_f32_16x16x32_bf16 v[110:113], v[134:137], v[196:199], v[110:113]
	v_mfma_f32_16x16x32_bf16 v[94:97], v[134:137], v[204:207], v[94:97]
	v_mfma_f32_16x16x32_bf16 v[90:93], v[142:145], v[204:207], v[90:93]
	v_mfma_f32_16x16x32_bf16 v[74:77], v[142:145], v[232:235], v[74:77]
	v_mfma_f32_16x16x32_bf16 v[78:81], v[134:137], v[232:235], v[78:81]
	s_setprio 0
	s_setprio 1
	v_mfma_f32_16x16x32_bf16 v[118:121], v[146:149], v[184:187], v[118:121]
	v_mfma_f32_16x16x32_bf16 v[114:117], v[176:179], v[184:187], v[114:117]
	v_mfma_f32_16x16x32_bf16 v[98:101], v[176:179], v[192:195], v[98:101]
	v_mfma_f32_16x16x32_bf16 v[102:105], v[146:149], v[192:195], v[102:105]
	v_mfma_f32_16x16x32_bf16 v[86:89], v[146:149], v[200:203], v[86:89]
	v_mfma_f32_16x16x32_bf16 v[82:85], v[176:179], v[200:203], v[82:85]
	v_mfma_f32_16x16x32_bf16 v[66:69], v[176:179], v[228:231], v[66:69]
	v_mfma_f32_16x16x32_bf16 v[70:73], v[146:149], v[228:231], v[70:73]
	v_mfma_f32_16x16x32_bf16 v[118:121], v[150:153], v[188:191], v[118:121]
	v_mfma_f32_16x16x32_bf16 v[114:117], v[180:183], v[188:191], v[114:117]
	v_mfma_f32_16x16x32_bf16 v[98:101], v[180:183], v[196:199], v[98:101]
	v_mfma_f32_16x16x32_bf16 v[102:105], v[150:153], v[196:199], v[102:105]
	v_mfma_f32_16x16x32_bf16 v[86:89], v[150:153], v[204:207], v[86:89]
	v_mfma_f32_16x16x32_bf16 v[82:85], v[180:183], v[204:207], v[82:85]
	v_mfma_f32_16x16x32_bf16 v[66:69], v[180:183], v[232:235], v[66:69]
	v_mfma_f32_16x16x32_bf16 v[70:73], v[150:153], v[232:235], v[70:73]
	s_setprio 0
	s_barrier
	s_add_i32 s30, s56, s36
	v_lshl_add_u64 v[162:163], v[162:163], 0, s[86:87]
	s_mov_b32 m0, s30
	ds_read_b128 v[184:187], v226 offset:49152
	ds_read_b128 v[188:191], v226 offset:50176
	ds_read_b128 v[192:195], v226 offset:51200
	ds_read_b128 v[196:199], v226 offset:52224
	ds_read_b128 v[200:203], v226 offset:53248
	ds_read_b128 v[204:207], v226 offset:54272
	ds_read_b128 v[228:231], v226 offset:55296
	ds_read_b128 v[232:235], v226 offset:56320
	global_load_lds_dwordx4 v[162:163], off
	s_add_i32 m0, s30, 0x2000
	s_add_u32 s28, s28, 0x40080
	v_lshl_add_u64 v[162:163], v[208:209], 0, s[86:87]
	s_addc_u32 s29, s29, 0
	s_add_i32 s30, s57, s36
	global_load_lds_dwordx4 v[162:163], off
	v_lshl_add_u64 v[162:163], s[28:29], 0, v[0:1]
	s_mov_b32 m0, s30
	s_nop 0
	global_load_lds_dwordx4 v[162:163], off
	v_lshl_add_u64 v[162:163], s[28:29], 0, v[158:159]
	s_add_i32 m0, s30, 0x2000
	s_nop 0
	global_load_lds_dwordx4 v[162:163], off
	v_lshl_add_u64 v[162:163], v[214:215], 0, s[86:87]
	s_mov_b32 m0, s44
	s_nop 0
	global_load_lds_dwordx4 v[162:163], off
	v_lshl_add_u64 v[162:163], v[216:217], 0, s[86:87]
	s_mov_b32 m0, s45
	s_nop 0
	global_load_lds_dwordx4 v[162:163], off
	s_waitcnt vmcnt(8)
	s_waitcnt lgkmcnt(0)
	s_barrier
	s_setprio 1
	s_waitcnt lgkmcnt(0)
	v_mfma_f32_16x16x32_bf16 v[62:65], v[130:133], v[184:187], v[62:65]
	v_mfma_f32_16x16x32_bf16 v[58:61], v[138:141], v[184:187], v[58:61]
	v_mfma_f32_16x16x32_bf16 v[42:45], v[138:141], v[192:195], v[42:45]
	v_mfma_f32_16x16x32_bf16 v[46:49], v[130:133], v[192:195], v[46:49]
	v_mfma_f32_16x16x32_bf16 v[30:33], v[130:133], v[200:203], v[30:33]
	v_mfma_f32_16x16x32_bf16 v[26:29], v[138:141], v[200:203], v[26:29]
	v_mfma_f32_16x16x32_bf16 v[10:13], v[138:141], v[228:231], v[10:13]
	v_mfma_f32_16x16x32_bf16 v[14:17], v[130:133], v[228:231], v[14:17]
	v_mfma_f32_16x16x32_bf16 v[62:65], v[134:137], v[188:191], v[62:65]
	v_mfma_f32_16x16x32_bf16 v[58:61], v[142:145], v[188:191], v[58:61]
	v_mfma_f32_16x16x32_bf16 v[42:45], v[142:145], v[196:199], v[42:45]
	v_mfma_f32_16x16x32_bf16 v[46:49], v[134:137], v[196:199], v[46:49]
	v_mfma_f32_16x16x32_bf16 v[30:33], v[134:137], v[204:207], v[30:33]
	v_mfma_f32_16x16x32_bf16 v[26:29], v[142:145], v[204:207], v[26:29]
	v_mfma_f32_16x16x32_bf16 v[10:13], v[142:145], v[232:235], v[10:13]
	v_mfma_f32_16x16x32_bf16 v[14:17], v[134:137], v[232:235], v[14:17]
	s_setprio 0
	s_setprio 1
	v_mfma_f32_16x16x32_bf16 v[54:57], v[146:149], v[184:187], v[54:57]
	v_mfma_f32_16x16x32_bf16 v[50:53], v[176:179], v[184:187], v[50:53]
	v_mfma_f32_16x16x32_bf16 v[34:37], v[176:179], v[192:195], v[34:37]
	v_mfma_f32_16x16x32_bf16 v[38:41], v[146:149], v[192:195], v[38:41]
	v_mfma_f32_16x16x32_bf16 v[22:25], v[146:149], v[200:203], v[22:25]
	v_mfma_f32_16x16x32_bf16 v[18:21], v[176:179], v[200:203], v[18:21]
	v_mfma_f32_16x16x32_bf16 v[2:5], v[176:179], v[228:231], v[2:5]
	v_mfma_f32_16x16x32_bf16 v[6:9], v[146:149], v[228:231], v[6:9]
	v_mfma_f32_16x16x32_bf16 v[54:57], v[150:153], v[188:191], v[54:57]
	v_mfma_f32_16x16x32_bf16 v[50:53], v[180:183], v[188:191], v[50:53]
	v_mfma_f32_16x16x32_bf16 v[34:37], v[180:183], v[196:199], v[34:37]
	v_mfma_f32_16x16x32_bf16 v[38:41], v[150:153], v[196:199], v[38:41]
	v_mfma_f32_16x16x32_bf16 v[22:25], v[150:153], v[204:207], v[22:25]
	v_mfma_f32_16x16x32_bf16 v[18:21], v[180:183], v[204:207], v[18:21]
	v_mfma_f32_16x16x32_bf16 v[2:5], v[180:183], v[232:235], v[2:5]
	v_mfma_f32_16x16x32_bf16 v[6:9], v[150:153], v[232:235], v[6:9]
	s_setprio 0
	s_barrier
	s_add_i32 s55, s55, 2
	s_add_u32 s8, s8, 0x100
	s_addc_u32 s9, s9, 0
	s_add_u32 s53, s53, 0x100
	s_addc_u32 s54, s54, 0
	s_cmp_gt_u32 s55, 13
	s_cbranch_scc0 .LBB0_809
	s_and_b64 vcc, exec, s[10:11]
	s_cbranch_vccz .LBB0_812
	s_barrier

.LBB0_1343:
	s_add_u32 s6, s26, 0x80
	s_addc_u32 s7, s27, 0
	s_add_u32 s26, s24, 0x100
	s_addc_u32 s27, s25, 0
	s_mov_b32 s24, 0
	s_add_i32 s47, s24, 2
	s_add_u32 s48, s6, 0x80
	s_addc_u32 s25, s7, 0
	s_add_i32 s50, 0, 0x10000
	s_cmp_eq_u32 s41, s24
	s_cselect_b32 s25, s21, s25
	s_cselect_b32 s24, s20, s48
	s_cselect_b32 s49, s23, s27
	s_cselect_b32 s48, s22, s26
	s_add_i32 s51, 0, 0x14000
	v_add_u32_e32 v142, s50, v197
	v_add_u32_e32 v162, s51, v197
	ds_read_b128 v[122:125], v142
	ds_read_b128 v[134:137], v142 offset:1024
	ds_read_b128 v[138:141], v142 offset:2048
	ds_read_b128 v[142:145], v142 offset:3072
	ds_read_b128 v[146:149], v162
	ds_read_b128 v[150:153], v162 offset:1024
	ds_read_b128 v[154:157], v162 offset:2048
	ds_read_b128 v[178:181], v162 offset:3072
	v_lshl_add_u64 v[162:163], s[6:7], 0, v[174:175]
	s_add_i32 m0, s31, 0xc000
	ds_read_b128 v[182:185], v199
	ds_read_b128 v[186:189], v199 offset:1024
	ds_read_b128 v[190:193], v199 offset:2048
	ds_read_b128 v[200:203], v199 offset:3072
	ds_read_b128 v[204:207], v199 offset:4096
	ds_read_b128 v[224:227], v199 offset:5120
	ds_read_b128 v[228:231], v199 offset:6144
	ds_read_b128 v[232:235], v199 offset:7168
	global_load_lds_dwordx4 v[162:163], off
	v_lshl_add_u64 v[162:163], s[6:7], 0, v[176:177]
	s_add_i32 m0, s31, 0xe000
	s_nop 0
	global_load_lds_dwordx4 v[162:163], off
	s_waitcnt vmcnt(16)
	s_waitcnt lgkmcnt(0)
	s_barrier
	s_setprio 1
	s_waitcnt lgkmcnt(0)
	v_mfma_f32_16x16x32_bf16 v[130:133], v[122:125], v[182:185], 0
	v_mfma_f32_16x16x32_bf16 v[126:129], v[138:141], v[182:185], 0
	v_mfma_f32_16x16x32_bf16 v[106:109], v[138:141], v[190:193], 0
	v_mfma_f32_16x16x32_bf16 v[110:113], v[122:125], v[190:193], 0
	v_mfma_f32_16x16x32_bf16 v[94:97], v[122:125], v[204:207], 0
	v_mfma_f32_16x16x32_bf16 v[90:93], v[138:141], v[204:207], 0
	v_mfma_f32_16x16x32_bf16 v[74:77], v[138:141], v[228:231], 0
	v_mfma_f32_16x16x32_bf16 v[78:81], v[122:125], v[228:231], 0
	v_mfma_f32_16x16x32_bf16 v[130:133], v[134:137], v[186:189], v[130:133]
	v_mfma_f32_16x16x32_bf16 v[126:129], v[142:145], v[186:189], v[126:129]
	v_mfma_f32_16x16x32_bf16 v[106:109], v[142:145], v[200:203], v[106:109]
	v_mfma_f32_16x16x32_bf16 v[110:113], v[134:137], v[200:203], v[110:113]
	v_mfma_f32_16x16x32_bf16 v[94:97], v[134:137], v[224:227], v[94:97]
	v_mfma_f32_16x16x32_bf16 v[90:93], v[142:145], v[224:227], v[90:93]
	v_mfma_f32_16x16x32_bf16 v[74:77], v[142:145], v[232:235], v[74:77]
	v_mfma_f32_16x16x32_bf16 v[78:81], v[134:137], v[232:235], v[78:81]
	s_setprio 0
	s_setprio 1
	v_mfma_f32_16x16x32_bf16 v[118:121], v[146:149], v[182:185], 0
	v_mfma_f32_16x16x32_bf16 v[114:117], v[154:157], v[182:185], 0
	v_mfma_f32_16x16x32_bf16 v[98:101], v[154:157], v[190:193], 0
	v_mfma_f32_16x16x32_bf16 v[102:105], v[146:149], v[190:193], 0
	v_mfma_f32_16x16x32_bf16 v[86:89], v[146:149], v[204:207], 0
	v_mfma_f32_16x16x32_bf16 v[82:85], v[154:157], v[204:207], 0
	v_mfma_f32_16x16x32_bf16 v[66:69], v[154:157], v[228:231], 0
	v_mfma_f32_16x16x32_bf16 v[70:73], v[146:149], v[228:231], 0
	v_mfma_f32_16x16x32_bf16 v[118:121], v[150:153], v[186:189], v[118:121]
	v_mfma_f32_16x16x32_bf16 v[114:117], v[178:181], v[186:189], v[114:117]
	v_mfma_f32_16x16x32_bf16 v[98:101], v[178:181], v[200:203], v[98:101]
	v_mfma_f32_16x16x32_bf16 v[102:105], v[150:153], v[200:203], v[102:105]
	v_mfma_f32_16x16x32_bf16 v[86:89], v[150:153], v[224:227], v[86:89]
	v_mfma_f32_16x16x32_bf16 v[82:85], v[178:181], v[224:227], v[82:85]
	v_mfma_f32_16x16x32_bf16 v[66:69], v[178:181], v[232:235], v[66:69]
	v_mfma_f32_16x16x32_bf16 v[70:73], v[150:153], v[232:235], v[70:73]
	s_setprio 0
	s_barrier
	s_add_i32 s50, s50, s30
	v_lshl_add_u64 v[162:163], s[48:49], 0, v[0:1]
	s_mov_b32 m0, s50
	ds_read_b128 v[182:185], v199 offset:16384
	ds_read_b128 v[186:189], v199 offset:17408
	ds_read_b128 v[190:193], v199 offset:18432
	ds_read_b128 v[200:203], v199 offset:19456
	ds_read_b128 v[204:207], v199 offset:20480
	ds_read_b128 v[224:227], v199 offset:21504
	ds_read_b128 v[228:231], v199 offset:22528
	ds_read_b128 v[232:235], v199 offset:23552
	global_load_lds_dwordx4 v[162:163], off
	s_add_i32 m0, s50, 0x2000
	v_lshl_add_u64 v[194:195], s[48:49], 0, v[160:161]
	s_add_u32 s48, s48, s28
	s_addc_u32 s49, s49, 0
	s_add_i32 s50, s51, s30
	global_load_lds_dwordx4 v[194:195], off
	v_lshl_add_u64 v[208:209], s[48:49], 0, v[0:1]
	s_mov_b32 m0, s50
	v_lshl_add_u64 v[214:215], s[48:49], 0, v[160:161]
	global_load_lds_dwordx4 v[208:209], off
	s_add_i32 m0, s50, 0x2000
	v_lshl_add_u64 v[216:217], s[24:25], 0, v[172:173]
	global_load_lds_dwordx4 v[214:215], off
	s_mov_b32 m0, s31
	v_lshl_add_u64 v[236:237], s[24:25], 0, v[170:171]
	global_load_lds_dwordx4 v[216:217], off
	s_mov_b32 m0, s34
	s_nop 0
	global_load_lds_dwordx4 v[236:237], off
	s_cmp_eq_u32 s42, 1
	s_cbranch_scc1 .Lrs_peel_w8
	s_waitcnt vmcnt(16)
	s_branch .Lrs_peel_wj

.Lrs_peel_wj:
	s_waitcnt lgkmcnt(0)
	s_barrier
	s_setprio 1
	s_waitcnt lgkmcnt(0)
	v_mfma_f32_16x16x32_bf16 v[62:65], v[122:125], v[182:185], 0
	v_mfma_f32_16x16x32_bf16 v[58:61], v[138:141], v[182:185], 0
	v_mfma_f32_16x16x32_bf16 v[42:45], v[138:141], v[190:193], 0
	v_mfma_f32_16x16x32_bf16 v[46:49], v[122:125], v[190:193], 0
	v_mfma_f32_16x16x32_bf16 v[30:33], v[122:125], v[204:207], 0
	v_mfma_f32_16x16x32_bf16 v[26:29], v[138:141], v[204:207], 0
	v_mfma_f32_16x16x32_bf16 v[10:13], v[138:141], v[228:231], 0
	v_mfma_f32_16x16x32_bf16 v[14:17], v[122:125], v[228:231], 0
	v_mfma_f32_16x16x32_bf16 v[62:65], v[134:137], v[186:189], v[62:65]
	v_mfma_f32_16x16x32_bf16 v[58:61], v[142:145], v[186:189], v[58:61]
	v_mfma_f32_16x16x32_bf16 v[42:45], v[142:145], v[200:203], v[42:45]
	v_mfma_f32_16x16x32_bf16 v[46:49], v[134:137], v[200:203], v[46:49]
	v_mfma_f32_16x16x32_bf16 v[30:33], v[134:137], v[224:227], v[30:33]
	v_mfma_f32_16x16x32_bf16 v[26:29], v[142:145], v[224:227], v[26:29]
	v_mfma_f32_16x16x32_bf16 v[10:13], v[142:145], v[232:235], v[10:13]
	v_mfma_f32_16x16x32_bf16 v[14:17], v[134:137], v[232:235], v[14:17]
	s_setprio 0
	s_setprio 1
	v_mfma_f32_16x16x32_bf16 v[54:57], v[146:149], v[182:185], 0
	v_mfma_f32_16x16x32_bf16 v[50:53], v[154:157], v[182:185], 0
	v_mfma_f32_16x16x32_bf16 v[34:37], v[154:157], v[190:193], 0
	v_mfma_f32_16x16x32_bf16 v[38:41], v[146:149], v[190:193], 0
	v_mfma_f32_16x16x32_bf16 v[22:25], v[146:149], v[204:207], 0
	v_mfma_f32_16x16x32_bf16 v[18:21], v[154:157], v[204:207], 0
	v_mfma_f32_16x16x32_bf16 v[2:5], v[154:157], v[228:231], 0
	v_mfma_f32_16x16x32_bf16 v[6:9], v[146:149], v[228:231], 0
	v_mfma_f32_16x16x32_bf16 v[54:57], v[150:153], v[186:189], v[54:57]
	v_mfma_f32_16x16x32_bf16 v[50:53], v[178:181], v[186:189], v[50:53]
	v_mfma_f32_16x16x32_bf16 v[34:37], v[178:181], v[200:203], v[34:37]
	v_mfma_f32_16x16x32_bf16 v[38:41], v[150:153], v[200:203], v[38:41]
	v_mfma_f32_16x16x32_bf16 v[22:25], v[150:153], v[224:227], v[22:25]
	v_mfma_f32_16x16x32_bf16 v[18:21], v[178:181], v[224:227], v[18:21]
	v_mfma_f32_16x16x32_bf16 v[2:5], v[178:181], v[232:235], v[2:5]
	v_mfma_f32_16x16x32_bf16 v[6:9], v[150:153], v[232:235], v[6:9]
	s_setprio 0
	s_barrier
	s_add_i32 s48, 0, 0x18000
	s_add_i32 s49, 0, 0x1c000
	v_add_u32_e32 v142, s48, v197
	v_add_u32_e32 v164, s49, v197
	ds_read_b128 v[122:125], v142
	ds_read_b128 v[134:137], v142 offset:1024
	ds_read_b128 v[138:141], v142 offset:2048
	ds_read_b128 v[142:145], v142 offset:3072
	ds_read_b128 v[146:149], v164
	ds_read_b128 v[150:153], v164 offset:1024
	ds_read_b128 v[154:157], v164 offset:2048
	ds_read_b128 v[178:181], v164 offset:3072
	s_add_u32 s24, s24, s10
	s_addc_u32 s25, s25, 0
	s_mov_b32 m0, s35
	v_lshl_add_u64 v[238:239], s[24:25], 0, v[172:173]
	ds_read_b128 v[182:185], v199 offset:32768
	ds_read_b128 v[186:189], v199 offset:33792
	ds_read_b128 v[190:193], v199 offset:34816
	ds_read_b128 v[200:203], v199 offset:35840
	ds_read_b128 v[204:207], v199 offset:36864
	ds_read_b128 v[224:227], v199 offset:37888
	ds_read_b128 v[228:231], v199 offset:38912
	ds_read_b128 v[232:235], v199 offset:39936
	global_load_lds_dwordx4 v[238:239], off
	v_lshl_add_u64 v[238:239], s[24:25], 0, v[170:171]
	s_mov_b32 m0, s36
	s_nop 0
	global_load_lds_dwordx4 v[238:239], off
	s_waitcnt vmcnt(8)
	s_waitcnt lgkmcnt(0)
	s_barrier
	s_setprio 1
	s_waitcnt lgkmcnt(0)
	v_mfma_f32_16x16x32_bf16 v[130:133], v[122:125], v[182:185], v[130:133]
	v_mfma_f32_16x16x32_bf16 v[126:129], v[138:141], v[182:185], v[126:129]
	v_mfma_f32_16x16x32_bf16 v[106:109], v[138:141], v[190:193], v[106:109]
	v_mfma_f32_16x16x32_bf16 v[110:113], v[122:125], v[190:193], v[110:113]
	v_mfma_f32_16x16x32_bf16 v[94:97], v[122:125], v[204:207], v[94:97]
	v_mfma_f32_16x16x32_bf16 v[90:93], v[138:141], v[204:207], v[90:93]
	v_mfma_f32_16x16x32_bf16 v[74:77], v[138:141], v[228:231], v[74:77]
	v_mfma_f32_16x16x32_bf16 v[78:81], v[122:125], v[228:231], v[78:81]
	v_mfma_f32_16x16x32_bf16 v[130:133], v[134:137], v[186:189], v[130:133]
	v_mfma_f32_16x16x32_bf16 v[126:129], v[142:145], v[186:189], v[126:129]
	v_mfma_f32_16x16x32_bf16 v[106:109], v[142:145], v[200:203], v[106:109]
	v_mfma_f32_16x16x32_bf16 v[110:113], v[134:137], v[200:203], v[110:113]
	v_mfma_f32_16x16x32_bf16 v[94:97], v[134:137], v[224:227], v[94:97]
	v_mfma_f32_16x16x32_bf16 v[90:93], v[142:145], v[224:227], v[90:93]
	v_mfma_f32_16x16x32_bf16 v[74:77], v[142:145], v[232:235], v[74:77]
	v_mfma_f32_16x16x32_bf16 v[78:81], v[134:137], v[232:235], v[78:81]
	s_setprio 0
	s_setprio 1
	v_mfma_f32_16x16x32_bf16 v[118:121], v[146:149], v[182:185], v[118:121]
	v_mfma_f32_16x16x32_bf16 v[114:117], v[154:157], v[182:185], v[114:117]
	v_mfma_f32_16x16x32_bf16 v[98:101], v[154:157], v[190:193], v[98:101]
	v_mfma_f32_16x16x32_bf16 v[102:105], v[146:149], v[190:193], v[102:105]
	v_mfma_f32_16x16x32_bf16 v[86:89], v[146:149], v[204:207], v[86:89]
	v_mfma_f32_16x16x32_bf16 v[82:85], v[154:157], v[204:207], v[82:85]
	v_mfma_f32_16x16x32_bf16 v[66:69], v[154:157], v[228:231], v[66:69]
	v_mfma_f32_16x16x32_bf16 v[70:73], v[146:149], v[228:231], v[70:73]
	v_mfma_f32_16x16x32_bf16 v[118:121], v[150:153], v[186:189], v[118:121]
	v_mfma_f32_16x16x32_bf16 v[114:117], v[178:181], v[186:189], v[114:117]
	v_mfma_f32_16x16x32_bf16 v[98:101], v[178:181], v[200:203], v[98:101]
	v_mfma_f32_16x16x32_bf16 v[102:105], v[150:153], v[200:203], v[102:105]
	v_mfma_f32_16x16x32_bf16 v[86:89], v[150:153], v[224:227], v[86:89]
	v_mfma_f32_16x16x32_bf16 v[82:85], v[178:181], v[224:227], v[82:85]
	v_mfma_f32_16x16x32_bf16 v[66:69], v[178:181], v[232:235], v[66:69]
	v_mfma_f32_16x16x32_bf16 v[70:73], v[150:153], v[232:235], v[70:73]
	s_setprio 0
	s_barrier
	s_add_i32 s24, s48, s30
	v_lshl_add_u64 v[162:163], v[162:163], 0, s[86:87]
	s_mov_b32 m0, s24
	ds_read_b128 v[182:185], v199 offset:49152
	ds_read_b128 v[186:189], v199 offset:50176
	ds_read_b128 v[190:193], v199 offset:51200
	ds_read_b128 v[200:203], v199 offset:52224
	ds_read_b128 v[204:207], v199 offset:53248
	ds_read_b128 v[224:227], v199 offset:54272
	ds_read_b128 v[228:231], v199 offset:55296
	ds_read_b128 v[232:235], v199 offset:56320
	global_load_lds_dwordx4 v[162:163], off
	v_lshl_add_u64 v[162:163], v[194:195], 0, s[86:87]
	s_add_i32 m0, s24, 0x2000
	s_add_i32 s24, s49, s30
	global_load_lds_dwordx4 v[162:163], off
	v_lshl_add_u64 v[162:163], v[208:209], 0, s[86:87]
	s_mov_b32 m0, s24
	s_nop 0
	global_load_lds_dwordx4 v[162:163], off
	v_lshl_add_u64 v[162:163], v[214:215], 0, s[86:87]
	s_add_i32 m0, s24, 0x2000
	s_nop 0
	global_load_lds_dwordx4 v[162:163], off
	v_lshl_add_u64 v[162:163], v[216:217], 0, s[86:87]
	s_mov_b32 m0, s37
	s_nop 0
	global_load_lds_dwordx4 v[162:163], off
	v_lshl_add_u64 v[162:163], v[236:237], 0, s[86:87]
	s_mov_b32 m0, s38
	s_nop 0
	global_load_lds_dwordx4 v[162:163], off
	s_waitcnt vmcnt(8)
	s_waitcnt lgkmcnt(0)
	s_barrier
	s_setprio 1
	s_waitcnt lgkmcnt(0)
	v_mfma_f32_16x16x32_bf16 v[62:65], v[122:125], v[182:185], v[62:65]
	v_mfma_f32_16x16x32_bf16 v[58:61], v[138:141], v[182:185], v[58:61]
	v_mfma_f32_16x16x32_bf16 v[42:45], v[138:141], v[190:193], v[42:45]
	v_mfma_f32_16x16x32_bf16 v[46:49], v[122:125], v[190:193], v[46:49]
	v_mfma_f32_16x16x32_bf16 v[30:33], v[122:125], v[204:207], v[30:33]
	v_mfma_f32_16x16x32_bf16 v[26:29], v[138:141], v[204:207], v[26:29]
	v_mfma_f32_16x16x32_bf16 v[10:13], v[138:141], v[228:231], v[10:13]
	v_mfma_f32_16x16x32_bf16 v[14:17], v[122:125], v[228:231], v[14:17]
	v_mfma_f32_16x16x32_bf16 v[62:65], v[134:137], v[186:189], v[62:65]
	v_mfma_f32_16x16x32_bf16 v[58:61], v[142:145], v[186:189], v[58:61]
	v_mfma_f32_16x16x32_bf16 v[42:45], v[142:145], v[200:203], v[42:45]
	v_mfma_f32_16x16x32_bf16 v[46:49], v[134:137], v[200:203], v[46:49]
	v_mfma_f32_16x16x32_bf16 v[30:33], v[134:137], v[224:227], v[30:33]
	v_mfma_f32_16x16x32_bf16 v[26:29], v[142:145], v[224:227], v[26:29]
	v_mfma_f32_16x16x32_bf16 v[10:13], v[142:145], v[232:235], v[10:13]
	v_mfma_f32_16x16x32_bf16 v[14:17], v[134:137], v[232:235], v[14:17]
	s_setprio 0
	s_setprio 1
	v_mfma_f32_16x16x32_bf16 v[54:57], v[146:149], v[182:185], v[54:57]
	v_mfma_f32_16x16x32_bf16 v[50:53], v[154:157], v[182:185], v[50:53]
	v_mfma_f32_16x16x32_bf16 v[34:37], v[154:157], v[190:193], v[34:37]
	v_mfma_f32_16x16x32_bf16 v[38:41], v[146:149], v[190:193], v[38:41]
	v_mfma_f32_16x16x32_bf16 v[22:25], v[146:149], v[204:207], v[22:25]
	v_mfma_f32_16x16x32_bf16 v[18:21], v[154:157], v[204:207], v[18:21]
	v_mfma_f32_16x16x32_bf16 v[2:5], v[154:157], v[228:231], v[2:5]
	v_mfma_f32_16x16x32_bf16 v[6:9], v[146:149], v[228:231], v[6:9]
	v_mfma_f32_16x16x32_bf16 v[54:57], v[150:153], v[186:189], v[54:57]
	v_mfma_f32_16x16x32_bf16 v[50:53], v[178:181], v[186:189], v[50:53]
	v_mfma_f32_16x16x32_bf16 v[34:37], v[178:181], v[200:203], v[34:37]
	v_mfma_f32_16x16x32_bf16 v[38:41], v[150:153], v[200:203], v[38:41]
	v_mfma_f32_16x16x32_bf16 v[22:25], v[150:153], v[224:227], v[22:25]
	v_mfma_f32_16x16x32_bf16 v[18:21], v[178:181], v[224:227], v[18:21]
	v_mfma_f32_16x16x32_bf16 v[2:5], v[178:181], v[232:235], v[2:5]
	v_mfma_f32_16x16x32_bf16 v[6:9], v[150:153], v[232:235], v[6:9]
	s_setprio 0
	s_barrier
	s_add_u32 s6, s6, 0x100
	s_addc_u32 s7, s7, 0
	s_add_u32 s26, s26, 0x100
	s_addc_u32 s27, s27, 0
	s_cmp_ge_u32 s47, s40
	s_mov_b32 s24, s47
	s_cbranch_scc0 .LBB0_1344
.LBB0_1344:
	s_add_i32 s47, s24, 2
	s_add_u32 s48, s6, 0x80
	s_addc_u32 s25, s7, 0
	s_add_i32 s50, 0, 0x10000
	s_cmp_eq_u32 s41, s24
	s_cselect_b32 s25, s21, s25
	s_cselect_b32 s24, s20, s48
	s_cselect_b32 s49, s23, s27
	s_cselect_b32 s48, s22, s26
	s_add_i32 s51, 0, 0x14000
	v_add_u32_e32 v142, s50, v197
	v_add_u32_e32 v162, s51, v197
	ds_read_b128 v[122:125], v142
	ds_read_b128 v[134:137], v142 offset:1024
	ds_read_b128 v[138:141], v142 offset:2048
	ds_read_b128 v[142:145], v142 offset:3072
	ds_read_b128 v[146:149], v162
	ds_read_b128 v[150:153], v162 offset:1024
	ds_read_b128 v[154:157], v162 offset:2048
	ds_read_b128 v[178:181], v162 offset:3072
	v_lshl_add_u64 v[162:163], s[6:7], 0, v[174:175]
	s_add_i32 m0, s31, 0xc000
	ds_read_b128 v[182:185], v199
	ds_read_b128 v[186:189], v199 offset:1024
	ds_read_b128 v[190:193], v199 offset:2048
	ds_read_b128 v[200:203], v199 offset:3072
	ds_read_b128 v[204:207], v199 offset:4096
	ds_read_b128 v[224:227], v199 offset:5120
	ds_read_b128 v[228:231], v199 offset:6144
	ds_read_b128 v[232:235], v199 offset:7168
	global_load_lds_dwordx4 v[162:163], off
	v_lshl_add_u64 v[162:163], s[6:7], 0, v[176:177]
	s_add_i32 m0, s31, 0xe000
	s_nop 0
	global_load_lds_dwordx4 v[162:163], off
	s_waitcnt vmcnt(8)
	s_waitcnt lgkmcnt(0)
	s_barrier
	s_setprio 1
	s_waitcnt lgkmcnt(0)
	v_mfma_f32_16x16x32_bf16 v[130:133], v[122:125], v[182:185], v[130:133]
	v_mfma_f32_16x16x32_bf16 v[126:129], v[138:141], v[182:185], v[126:129]
	v_mfma_f32_16x16x32_bf16 v[106:109], v[138:141], v[190:193], v[106:109]
	v_mfma_f32_16x16x32_bf16 v[110:113], v[122:125], v[190:193], v[110:113]
	v_mfma_f32_16x16x32_bf16 v[94:97], v[122:125], v[204:207], v[94:97]
	v_mfma_f32_16x16x32_bf16 v[90:93], v[138:141], v[204:207], v[90:93]
	v_mfma_f32_16x16x32_bf16 v[74:77], v[138:141], v[228:231], v[74:77]
	v_mfma_f32_16x16x32_bf16 v[78:81], v[122:125], v[228:231], v[78:81]
	v_mfma_f32_16x16x32_bf16 v[130:133], v[134:137], v[186:189], v[130:133]
	v_mfma_f32_16x16x32_bf16 v[126:129], v[142:145], v[186:189], v[126:129]
	v_mfma_f32_16x16x32_bf16 v[106:109], v[142:145], v[200:203], v[106:109]
	v_mfma_f32_16x16x32_bf16 v[110:113], v[134:137], v[200:203], v[110:113]
	v_mfma_f32_16x16x32_bf16 v[94:97], v[134:137], v[224:227], v[94:97]
	v_mfma_f32_16x16x32_bf16 v[90:93], v[142:145], v[224:227], v[90:93]
	v_mfma_f32_16x16x32_bf16 v[74:77], v[142:145], v[232:235], v[74:77]
	v_mfma_f32_16x16x32_bf16 v[78:81], v[134:137], v[232:235], v[78:81]
	s_setprio 0
	s_setprio 1
	v_mfma_f32_16x16x32_bf16 v[118:121], v[146:149], v[182:185], v[118:121]
	v_mfma_f32_16x16x32_bf16 v[114:117], v[154:157], v[182:185], v[114:117]
	v_mfma_f32_16x16x32_bf16 v[98:101], v[154:157], v[190:193], v[98:101]
	v_mfma_f32_16x16x32_bf16 v[102:105], v[146:149], v[190:193], v[102:105]
	v_mfma_f32_16x16x32_bf16 v[86:89], v[146:149], v[204:207], v[86:89]
	v_mfma_f32_16x16x32_bf16 v[82:85], v[154:157], v[204:207], v[82:85]
	v_mfma_f32_16x16x32_bf16 v[66:69], v[154:157], v[228:231], v[66:69]
	v_mfma_f32_16x16x32_bf16 v[70:73], v[146:149], v[228:231], v[70:73]
	v_mfma_f32_16x16x32_bf16 v[118:121], v[150:153], v[186:189], v[118:121]
	v_mfma_f32_16x16x32_bf16 v[114:117], v[178:181], v[186:189], v[114:117]
	v_mfma_f32_16x16x32_bf16 v[98:101], v[178:181], v[200:203], v[98:101]
	v_mfma_f32_16x16x32_bf16 v[102:105], v[150:153], v[200:203], v[102:105]
	v_mfma_f32_16x16x32_bf16 v[86:89], v[150:153], v[224:227], v[86:89]
	v_mfma_f32_16x16x32_bf16 v[82:85], v[178:181], v[224:227], v[82:85]
	v_mfma_f32_16x16x32_bf16 v[66:69], v[178:181], v[232:235], v[66:69]
	v_mfma_f32_16x16x32_bf16 v[70:73], v[150:153], v[232:235], v[70:73]
	s_setprio 0
	s_barrier
	s_add_i32 s50, s50, s30
	v_lshl_add_u64 v[162:163], s[48:49], 0, v[0:1]
	s_mov_b32 m0, s50
	ds_read_b128 v[182:185], v199 offset:16384
	ds_read_b128 v[186:189], v199 offset:17408
	ds_read_b128 v[190:193], v199 offset:18432
	ds_read_b128 v[200:203], v199 offset:19456
	ds_read_b128 v[204:207], v199 offset:20480
	ds_read_b128 v[224:227], v199 offset:21504
	ds_read_b128 v[228:231], v199 offset:22528
	ds_read_b128 v[232:235], v199 offset:23552
	global_load_lds_dwordx4 v[162:163], off
	s_add_i32 m0, s50, 0x2000
	v_lshl_add_u64 v[194:195], s[48:49], 0, v[160:161]
	s_add_u32 s48, s48, s28
	s_addc_u32 s49, s49, 0
	s_add_i32 s50, s51, s30
	global_load_lds_dwordx4 v[194:195], off
	v_lshl_add_u64 v[208:209], s[48:49], 0, v[0:1]
	s_mov_b32 m0, s50
	v_lshl_add_u64 v[214:215], s[48:49], 0, v[160:161]
	global_load_lds_dwordx4 v[208:209], off
	s_add_i32 m0, s50, 0x2000
	v_lshl_add_u64 v[216:217], s[24:25], 0, v[172:173]
	global_load_lds_dwordx4 v[214:215], off
	s_mov_b32 m0, s31
	v_lshl_add_u64 v[236:237], s[24:25], 0, v[170:171]
	global_load_lds_dwordx4 v[216:217], off
	s_mov_b32 m0, s34
	s_nop 0
	global_load_lds_dwordx4 v[236:237], off
	s_waitcnt vmcnt(8)
	s_waitcnt lgkmcnt(0)
	s_barrier
	s_setprio 1
	s_waitcnt lgkmcnt(0)
	v_mfma_f32_16x16x32_bf16 v[62:65], v[122:125], v[182:185], v[62:65]
	v_mfma_f32_16x16x32_bf16 v[58:61], v[138:141], v[182:185], v[58:61]
	v_mfma_f32_16x16x32_bf16 v[42:45], v[138:141], v[190:193], v[42:45]
	v_mfma_f32_16x16x32_bf16 v[46:49], v[122:125], v[190:193], v[46:49]
	v_mfma_f32_16x16x32_bf16 v[30:33], v[122:125], v[204:207], v[30:33]
	v_mfma_f32_16x16x32_bf16 v[26:29], v[138:141], v[204:207], v[26:29]
	v_mfma_f32_16x16x32_bf16 v[10:13], v[138:141], v[228:231], v[10:13]
	v_mfma_f32_16x16x32_bf16 v[14:17], v[122:125], v[228:231], v[14:17]
	v_mfma_f32_16x16x32_bf16 v[62:65], v[134:137], v[186:189], v[62:65]
	v_mfma_f32_16x16x32_bf16 v[58:61], v[142:145], v[186:189], v[58:61]
	v_mfma_f32_16x16x32_bf16 v[42:45], v[142:145], v[200:203], v[42:45]
	v_mfma_f32_16x16x32_bf16 v[46:49], v[134:137], v[200:203], v[46:49]
	v_mfma_f32_16x16x32_bf16 v[30:33], v[134:137], v[224:227], v[30:33]
	v_mfma_f32_16x16x32_bf16 v[26:29], v[142:145], v[224:227], v[26:29]
	v_mfma_f32_16x16x32_bf16 v[10:13], v[142:145], v[232:235], v[10:13]
	v_mfma_f32_16x16x32_bf16 v[14:17], v[134:137], v[232:235], v[14:17]
	s_setprio 0
	s_setprio 1
	v_mfma_f32_16x16x32_bf16 v[54:57], v[146:149], v[182:185], v[54:57]
	v_mfma_f32_16x16x32_bf16 v[50:53], v[154:157], v[182:185], v[50:53]
	v_mfma_f32_16x16x32_bf16 v[34:37], v[154:157], v[190:193], v[34:37]
	v_mfma_f32_16x16x32_bf16 v[38:41], v[146:149], v[190:193], v[38:41]
	v_mfma_f32_16x16x32_bf16 v[22:25], v[146:149], v[204:207], v[22:25]
	v_mfma_f32_16x16x32_bf16 v[18:21], v[154:157], v[204:207], v[18:21]
	v_mfma_f32_16x16x32_bf16 v[2:5], v[154:157], v[228:231], v[2:5]
	v_mfma_f32_16x16x32_bf16 v[6:9], v[146:149], v[228:231], v[6:9]
	v_mfma_f32_16x16x32_bf16 v[54:57], v[150:153], v[186:189], v[54:57]
	v_mfma_f32_16x16x32_bf16 v[50:53], v[178:181], v[186:189], v[50:53]
	v_mfma_f32_16x16x32_bf16 v[34:37], v[178:181], v[200:203], v[34:37]
	v_mfma_f32_16x16x32_bf16 v[38:41], v[150:153], v[200:203], v[38:41]
	v_mfma_f32_16x16x32_bf16 v[22:25], v[150:153], v[224:227], v[22:25]
	v_mfma_f32_16x16x32_bf16 v[18:21], v[178:181], v[224:227], v[18:21]
	v_mfma_f32_16x16x32_bf16 v[2:5], v[178:181], v[232:235], v[2:5]
	v_mfma_f32_16x16x32_bf16 v[6:9], v[150:153], v[232:235], v[6:9]
	s_setprio 0
	s_barrier
	s_add_i32 s48, 0, 0x18000
	s_add_i32 s49, 0, 0x1c000
	v_add_u32_e32 v142, s48, v197
	v_add_u32_e32 v164, s49, v197
	ds_read_b128 v[122:125], v142
	ds_read_b128 v[134:137], v142 offset:1024
	ds_read_b128 v[138:141], v142 offset:2048
	ds_read_b128 v[142:145], v142 offset:3072
	ds_read_b128 v[146:149], v164
	ds_read_b128 v[150:153], v164 offset:1024
	ds_read_b128 v[154:157], v164 offset:2048
	ds_read_b128 v[178:181], v164 offset:3072
	s_add_u32 s24, s24, s10
	s_addc_u32 s25, s25, 0
	s_mov_b32 m0, s35
	v_lshl_add_u64 v[238:239], s[24:25], 0, v[172:173]
	ds_read_b128 v[182:185], v199 offset:32768
	ds_read_b128 v[186:189], v199 offset:33792
	ds_read_b128 v[190:193], v199 offset:34816
	ds_read_b128 v[200:203], v199 offset:35840
	ds_read_b128 v[204:207], v199 offset:36864
	ds_read_b128 v[224:227], v199 offset:37888
	ds_read_b128 v[228:231], v199 offset:38912
	ds_read_b128 v[232:235], v199 offset:39936
	global_load_lds_dwordx4 v[238:239], off
	v_lshl_add_u64 v[238:239], s[24:25], 0, v[170:171]
	s_mov_b32 m0, s36
	s_nop 0
	global_load_lds_dwordx4 v[238:239], off
	s_waitcnt vmcnt(8)
	s_waitcnt lgkmcnt(0)
	s_barrier
	s_setprio 1
	s_waitcnt lgkmcnt(0)
	v_mfma_f32_16x16x32_bf16 v[130:133], v[122:125], v[182:185], v[130:133]
	v_mfma_f32_16x16x32_bf16 v[126:129], v[138:141], v[182:185], v[126:129]
	v_mfma_f32_16x16x32_bf16 v[106:109], v[138:141], v[190:193], v[106:109]
	v_mfma_f32_16x16x32_bf16 v[110:113], v[122:125], v[190:193], v[110:113]
	v_mfma_f32_16x16x32_bf16 v[94:97], v[122:125], v[204:207], v[94:97]
	v_mfma_f32_16x16x32_bf16 v[90:93], v[138:141], v[204:207], v[90:93]
	v_mfma_f32_16x16x32_bf16 v[74:77], v[138:141], v[228:231], v[74:77]
	v_mfma_f32_16x16x32_bf16 v[78:81], v[122:125], v[228:231], v[78:81]
	v_mfma_f32_16x16x32_bf16 v[130:133], v[134:137], v[186:189], v[130:133]
	v_mfma_f32_16x16x32_bf16 v[126:129], v[142:145], v[186:189], v[126:129]
	v_mfma_f32_16x16x32_bf16 v[106:109], v[142:145], v[200:203], v[106:109]
	v_mfma_f32_16x16x32_bf16 v[110:113], v[134:137], v[200:203], v[110:113]
	v_mfma_f32_16x16x32_bf16 v[94:97], v[134:137], v[224:227], v[94:97]
	v_mfma_f32_16x16x32_bf16 v[90:93], v[142:145], v[224:227], v[90:93]
	v_mfma_f32_16x16x32_bf16 v[74:77], v[142:145], v[232:235], v[74:77]
	v_mfma_f32_16x16x32_bf16 v[78:81], v[134:137], v[232:235], v[78:81]
	s_setprio 0
	s_setprio 1
	v_mfma_f32_16x16x32_bf16 v[118:121], v[146:149], v[182:185], v[118:121]
	v_mfma_f32_16x16x32_bf16 v[114:117], v[154:157], v[182:185], v[114:117]
	v_mfma_f32_16x16x32_bf16 v[98:101], v[154:157], v[190:193], v[98:101]
	v_mfma_f32_16x16x32_bf16 v[102:105], v[146:149], v[190:193], v[102:105]
	v_mfma_f32_16x16x32_bf16 v[86:89], v[146:149], v[204:207], v[86:89]
	v_mfma_f32_16x16x32_bf16 v[82:85], v[154:157], v[204:207], v[82:85]
	v_mfma_f32_16x16x32_bf16 v[66:69], v[154:157], v[228:231], v[66:69]
	v_mfma_f32_16x16x32_bf16 v[70:73], v[146:149], v[228:231], v[70:73]
	v_mfma_f32_16x16x32_bf16 v[118:121], v[150:153], v[186:189], v[118:121]
	v_mfma_f32_16x16x32_bf16 v[114:117], v[178:181], v[186:189], v[114:117]
	v_mfma_f32_16x16x32_bf16 v[98:101], v[178:181], v[200:203], v[98:101]
	v_mfma_f32_16x16x32_bf16 v[102:105], v[150:153], v[200:203], v[102:105]
	v_mfma_f32_16x16x32_bf16 v[86:89], v[150:153], v[224:227], v[86:89]
	v_mfma_f32_16x16x32_bf16 v[82:85], v[178:181], v[224:227], v[82:85]
	v_mfma_f32_16x16x32_bf16 v[66:69], v[178:181], v[232:235], v[66:69]
	v_mfma_f32_16x16x32_bf16 v[70:73], v[150:153], v[232:235], v[70:73]
	s_setprio 0
	s_barrier
	s_add_i32 s24, s48, s30
	v_lshl_add_u64 v[162:163], v[162:163], 0, s[86:87]
	s_mov_b32 m0, s24
	ds_read_b128 v[182:185], v199 offset:49152
	ds_read_b128 v[186:189], v199 offset:50176
	ds_read_b128 v[190:193], v199 offset:51200
	ds_read_b128 v[200:203], v199 offset:52224
	ds_read_b128 v[204:207], v199 offset:53248
	ds_read_b128 v[224:227], v199 offset:54272
	ds_read_b128 v[228:231], v199 offset:55296
	ds_read_b128 v[232:235], v199 offset:56320
	global_load_lds_dwordx4 v[162:163], off
	v_lshl_add_u64 v[162:163], v[194:195], 0, s[86:87]
	s_add_i32 m0, s24, 0x2000
	s_add_i32 s24, s49, s30
	global_load_lds_dwordx4 v[162:163], off
	v_lshl_add_u64 v[162:163], v[208:209], 0, s[86:87]
	s_mov_b32 m0, s24
	s_nop 0
	global_load_lds_dwordx4 v[162:163], off
	v_lshl_add_u64 v[162:163], v[214:215], 0, s[86:87]
	s_add_i32 m0, s24, 0x2000
	s_nop 0
	global_load_lds_dwordx4 v[162:163], off
	v_lshl_add_u64 v[162:163], v[216:217], 0, s[86:87]
	s_mov_b32 m0, s37
	s_nop 0
	global_load_lds_dwordx4 v[162:163], off
	v_lshl_add_u64 v[162:163], v[236:237], 0, s[86:87]
	s_mov_b32 m0, s38
	s_nop 0
	global_load_lds_dwordx4 v[162:163], off
	s_waitcnt vmcnt(8)
	s_waitcnt lgkmcnt(0)
	s_barrier
	s_setprio 1
	s_waitcnt lgkmcnt(0)
	v_mfma_f32_16x16x32_bf16 v[62:65], v[122:125], v[182:185], v[62:65]
	v_mfma_f32_16x16x32_bf16 v[58:61], v[138:141], v[182:185], v[58:61]
	v_mfma_f32_16x16x32_bf16 v[42:45], v[138:141], v[190:193], v[42:45]
	v_mfma_f32_16x16x32_bf16 v[46:49], v[122:125], v[190:193], v[46:49]
	v_mfma_f32_16x16x32_bf16 v[30:33], v[122:125], v[204:207], v[30:33]
	v_mfma_f32_16x16x32_bf16 v[26:29], v[138:141], v[204:207], v[26:29]
	v_mfma_f32_16x16x32_bf16 v[10:13], v[138:141], v[228:231], v[10:13]
	v_mfma_f32_16x16x32_bf16 v[14:17], v[122:125], v[228:231], v[14:17]
	v_mfma_f32_16x16x32_bf16 v[62:65], v[134:137], v[186:189], v[62:65]
	v_mfma_f32_16x16x32_bf16 v[58:61], v[142:145], v[186:189], v[58:61]
	v_mfma_f32_16x16x32_bf16 v[42:45], v[142:145], v[200:203], v[42:45]
	v_mfma_f32_16x16x32_bf16 v[46:49], v[134:137], v[200:203], v[46:49]
	v_mfma_f32_16x16x32_bf16 v[30:33], v[134:137], v[224:227], v[30:33]
	v_mfma_f32_16x16x32_bf16 v[26:29], v[142:145], v[224:227], v[26:29]
	v_mfma_f32_16x16x32_bf16 v[10:13], v[142:145], v[232:235], v[10:13]
	v_mfma_f32_16x16x32_bf16 v[14:17], v[134:137], v[232:235], v[14:17]
	s_setprio 0
	s_setprio 1
	v_mfma_f32_16x16x32_bf16 v[54:57], v[146:149], v[182:185], v[54:57]
	v_mfma_f32_16x16x32_bf16 v[50:53], v[154:157], v[182:185], v[50:53]
	v_mfma_f32_16x16x32_bf16 v[34:37], v[154:157], v[190:193], v[34:37]
	v_mfma_f32_16x16x32_bf16 v[38:41], v[146:149], v[190:193], v[38:41]
	v_mfma_f32_16x16x32_bf16 v[22:25], v[146:149], v[204:207], v[22:25]
	v_mfma_f32_16x16x32_bf16 v[18:21], v[154:157], v[204:207], v[18:21]
	v_mfma_f32_16x16x32_bf16 v[2:5], v[154:157], v[228:231], v[2:5]
	v_mfma_f32_16x16x32_bf16 v[6:9], v[146:149], v[228:231], v[6:9]
	v_mfma_f32_16x16x32_bf16 v[54:57], v[150:153], v[186:189], v[54:57]
	v_mfma_f32_16x16x32_bf16 v[50:53], v[178:181], v[186:189], v[50:53]
	v_mfma_f32_16x16x32_bf16 v[34:37], v[178:181], v[200:203], v[34:37]
	v_mfma_f32_16x16x32_bf16 v[38:41], v[150:153], v[200:203], v[38:41]
	v_mfma_f32_16x16x32_bf16 v[22:25], v[150:153], v[224:227], v[22:25]
	v_mfma_f32_16x16x32_bf16 v[18:21], v[178:181], v[224:227], v[18:21]
	v_mfma_f32_16x16x32_bf16 v[2:5], v[178:181], v[232:235], v[2:5]
	v_mfma_f32_16x16x32_bf16 v[6:9], v[150:153], v[232:235], v[6:9]
	s_setprio 0
	s_barrier
	s_add_u32 s6, s6, 0x100
	s_addc_u32 s7, s7, 0
	s_add_u32 s26, s26, 0x100
	s_addc_u32 s27, s27, 0
	s_cmp_ge_u32 s47, s40
	s_mov_b32 s24, s47
	s_cbranch_scc0 .LBB0_1344
	s_and_b64 vcc, exec, s[16:17]
	s_cbranch_vccz .LBB0_1347
	s_barrier

.Lgu_noy1:
	s_add_u32 s16, s4, 0xfffc0080
	s_addc_u32 s17, s5, -1
	s_add_i32 s42, 0, 0x10000
	s_cmp_eq_u32 s41, 12
	s_cselect_b32 s19, s11, s17
	s_cselect_b32 s18, s37, s16
	s_cselect_b32 s17, s9, s40
	s_cselect_b32 s16, s38, s39
	s_add_i32 s44, 0, 0x14000
	v_add_u32_e32 v142, s42, v195
	v_add_u32_e32 v162, s44, v195
	ds_read_b128 v[130:133], v142
	ds_read_b128 v[134:137], v142 offset:1024
	ds_read_b128 v[138:141], v142 offset:2048
	ds_read_b128 v[142:145], v142 offset:3072
	ds_read_b128 v[146:149], v162
	ds_read_b128 v[150:153], v162 offset:1024
	ds_read_b128 v[174:177], v162 offset:2048
	ds_read_b128 v[178:181], v162 offset:3072
	v_lshl_add_u64 v[162:163], s[4:5], 0, v[170:171]
	s_add_i32 m0, s23, 0xc000
	ds_read_b128 v[182:185], v199
	ds_read_b128 v[186:189], v199 offset:1024
	ds_read_b128 v[200:203], v199 offset:2048
	ds_read_b128 v[204:207], v199 offset:3072
	ds_read_b128 v[220:223], v199 offset:4096
	ds_read_b128 v[224:227], v199 offset:5120
	ds_read_b128 v[228:231], v199 offset:6144
	ds_read_b128 v[232:235], v199 offset:7168
	global_load_lds_dwordx4 v[162:163], off
	v_lshl_add_u64 v[162:163], s[4:5], 0, v[172:173]
	s_add_i32 m0, s23, 0xe000
	s_nop 0
	global_load_lds_dwordx4 v[162:163], off
	s_waitcnt vmcnt(16)
	s_waitcnt lgkmcnt(0)
	s_barrier
	s_setprio 1
	s_waitcnt lgkmcnt(0)
	v_mfma_f32_16x16x32_bf16 v[126:129], v[130:133], v[182:185], 0
	v_mfma_f32_16x16x32_bf16 v[118:121], v[138:141], v[182:185], 0
	v_mfma_f32_16x16x32_bf16 v[102:105], v[138:141], v[200:203], 0
	v_mfma_f32_16x16x32_bf16 v[110:113], v[130:133], v[200:203], 0
	v_mfma_f32_16x16x32_bf16 v[94:97], v[130:133], v[220:223], 0
	v_mfma_f32_16x16x32_bf16 v[86:89], v[138:141], v[220:223], 0
	v_mfma_f32_16x16x32_bf16 v[70:73], v[138:141], v[228:231], 0
	v_mfma_f32_16x16x32_bf16 v[78:81], v[130:133], v[228:231], 0
	v_mfma_f32_16x16x32_bf16 v[126:129], v[134:137], v[186:189], v[126:129]
	v_mfma_f32_16x16x32_bf16 v[118:121], v[142:145], v[186:189], v[118:121]
	v_mfma_f32_16x16x32_bf16 v[102:105], v[142:145], v[204:207], v[102:105]
	v_mfma_f32_16x16x32_bf16 v[110:113], v[134:137], v[204:207], v[110:113]
	v_mfma_f32_16x16x32_bf16 v[94:97], v[134:137], v[224:227], v[94:97]
	v_mfma_f32_16x16x32_bf16 v[86:89], v[142:145], v[224:227], v[86:89]
	v_mfma_f32_16x16x32_bf16 v[70:73], v[142:145], v[232:235], v[70:73]
	v_mfma_f32_16x16x32_bf16 v[78:81], v[134:137], v[232:235], v[78:81]
	s_setprio 0
	s_setprio 1
	v_mfma_f32_16x16x32_bf16 v[122:125], v[146:149], v[182:185], 0
	v_mfma_f32_16x16x32_bf16 v[114:117], v[174:177], v[182:185], 0
	v_mfma_f32_16x16x32_bf16 v[98:101], v[174:177], v[200:203], 0
	v_mfma_f32_16x16x32_bf16 v[106:109], v[146:149], v[200:203], 0
	v_mfma_f32_16x16x32_bf16 v[90:93], v[146:149], v[220:223], 0
	v_mfma_f32_16x16x32_bf16 v[82:85], v[174:177], v[220:223], 0
	v_mfma_f32_16x16x32_bf16 v[66:69], v[174:177], v[228:231], 0
	v_mfma_f32_16x16x32_bf16 v[74:77], v[146:149], v[228:231], 0
	v_mfma_f32_16x16x32_bf16 v[122:125], v[150:153], v[186:189], v[122:125]
	v_mfma_f32_16x16x32_bf16 v[114:117], v[178:181], v[186:189], v[114:117]
	v_mfma_f32_16x16x32_bf16 v[98:101], v[178:181], v[204:207], v[98:101]
	v_mfma_f32_16x16x32_bf16 v[106:109], v[150:153], v[204:207], v[106:109]
	v_mfma_f32_16x16x32_bf16 v[90:93], v[150:153], v[224:227], v[90:93]
	v_mfma_f32_16x16x32_bf16 v[82:85], v[178:181], v[224:227], v[82:85]
	v_mfma_f32_16x16x32_bf16 v[66:69], v[178:181], v[232:235], v[66:69]
	v_mfma_f32_16x16x32_bf16 v[74:77], v[150:153], v[232:235], v[74:77]
	s_setprio 0
	s_barrier
	s_add_i32 s42, s42, s22
	v_lshl_add_u64 v[162:163], s[16:17], 0, v[0:1]
	s_mov_b32 m0, s42
	ds_read_b128 v[182:185], v199 offset:16384
	ds_read_b128 v[186:189], v199 offset:17408
	ds_read_b128 v[200:203], v199 offset:18432
	ds_read_b128 v[204:207], v199 offset:19456
	ds_read_b128 v[220:223], v199 offset:20480
	ds_read_b128 v[224:227], v199 offset:21504
	ds_read_b128 v[228:231], v199 offset:22528
	ds_read_b128 v[232:235], v199 offset:23552
	global_load_lds_dwordx4 v[162:163], off
	s_add_i32 m0, s42, 0x2000
	s_add_u32 s42, s16, 0x40000
	v_lshl_add_u64 v[190:191], s[16:17], 0, v[154:155]
	s_addc_u32 s43, s17, 0
	s_add_i32 s44, s44, s22
	global_load_lds_dwordx4 v[190:191], off
	v_lshl_add_u64 v[196:197], s[42:43], 0, v[0:1]
	s_mov_b32 m0, s44
	v_lshl_add_u64 v[208:209], s[18:19], 0, v[156:157]
	global_load_lds_dwordx4 v[196:197], off
	v_lshl_add_u64 v[196:197], s[42:43], 0, v[154:155]
	s_add_i32 m0, s44, 0x2000
	s_nop 0
	global_load_lds_dwordx4 v[196:197], off
	v_lshl_add_u64 v[196:197], s[18:19], 0, v[158:159]
	s_mov_b32 m0, s23
	s_nop 0
	global_load_lds_dwordx4 v[196:197], off
	s_mov_b32 m0, s26
	s_nop 0
	global_load_lds_dwordx4 v[208:209], off
	s_cmp_eq_u32 s34, 1
	s_cbranch_scc1 .Lgu_peel_w8
	s_waitcnt vmcnt(16)
	s_branch .Lgu_peel_wj

.Lgu_peel_wj:
	s_waitcnt lgkmcnt(0)
	s_barrier
	s_setprio 1
	s_waitcnt lgkmcnt(0)
	v_mfma_f32_16x16x32_bf16 v[62:65], v[130:133], v[182:185], 0
	v_mfma_f32_16x16x32_bf16 v[54:57], v[138:141], v[182:185], 0
	v_mfma_f32_16x16x32_bf16 v[38:41], v[138:141], v[200:203], 0
	v_mfma_f32_16x16x32_bf16 v[46:49], v[130:133], v[200:203], 0
	v_mfma_f32_16x16x32_bf16 v[30:33], v[130:133], v[220:223], 0
	v_mfma_f32_16x16x32_bf16 v[22:25], v[138:141], v[220:223], 0
	v_mfma_f32_16x16x32_bf16 v[6:9], v[138:141], v[228:231], 0
	v_mfma_f32_16x16x32_bf16 v[14:17], v[130:133], v[228:231], 0
	v_mfma_f32_16x16x32_bf16 v[62:65], v[134:137], v[186:189], v[62:65]
	v_mfma_f32_16x16x32_bf16 v[54:57], v[142:145], v[186:189], v[54:57]
	v_mfma_f32_16x16x32_bf16 v[38:41], v[142:145], v[204:207], v[38:41]
	v_mfma_f32_16x16x32_bf16 v[46:49], v[134:137], v[204:207], v[46:49]
	v_mfma_f32_16x16x32_bf16 v[30:33], v[134:137], v[224:227], v[30:33]
	v_mfma_f32_16x16x32_bf16 v[22:25], v[142:145], v[224:227], v[22:25]
	v_mfma_f32_16x16x32_bf16 v[6:9], v[142:145], v[232:235], v[6:9]
	v_mfma_f32_16x16x32_bf16 v[14:17], v[134:137], v[232:235], v[14:17]
	s_setprio 0
	s_setprio 1
	v_mfma_f32_16x16x32_bf16 v[58:61], v[146:149], v[182:185], 0
	v_mfma_f32_16x16x32_bf16 v[50:53], v[174:177], v[182:185], 0
	v_mfma_f32_16x16x32_bf16 v[34:37], v[174:177], v[200:203], 0
	v_mfma_f32_16x16x32_bf16 v[42:45], v[146:149], v[200:203], 0
	v_mfma_f32_16x16x32_bf16 v[26:29], v[146:149], v[220:223], 0
	v_mfma_f32_16x16x32_bf16 v[18:21], v[174:177], v[220:223], 0
	v_mfma_f32_16x16x32_bf16 v[2:5], v[174:177], v[228:231], 0
	v_mfma_f32_16x16x32_bf16 v[10:13], v[146:149], v[228:231], 0
	v_mfma_f32_16x16x32_bf16 v[58:61], v[150:153], v[186:189], v[58:61]
	v_mfma_f32_16x16x32_bf16 v[50:53], v[178:181], v[186:189], v[50:53]
	v_mfma_f32_16x16x32_bf16 v[34:37], v[178:181], v[204:207], v[34:37]
	v_mfma_f32_16x16x32_bf16 v[42:45], v[150:153], v[204:207], v[42:45]
	v_mfma_f32_16x16x32_bf16 v[26:29], v[150:153], v[224:227], v[26:29]
	v_mfma_f32_16x16x32_bf16 v[18:21], v[178:181], v[224:227], v[18:21]
	v_mfma_f32_16x16x32_bf16 v[2:5], v[178:181], v[232:235], v[2:5]
	v_mfma_f32_16x16x32_bf16 v[10:13], v[150:153], v[232:235], v[10:13]
	s_setprio 0
	s_barrier
	s_add_i32 s42, 0, 0x18000
	s_add_i32 s43, 0, 0x1c000
	v_add_u32_e32 v142, s42, v195
	v_add_u32_e32 v164, s43, v195
	ds_read_b128 v[130:133], v142
	ds_read_b128 v[134:137], v142 offset:1024
	ds_read_b128 v[138:141], v142 offset:2048
	ds_read_b128 v[142:145], v142 offset:3072
	ds_read_b128 v[146:149], v164
	ds_read_b128 v[150:153], v164 offset:1024
	ds_read_b128 v[174:177], v164 offset:2048
	ds_read_b128 v[178:181], v164 offset:3072
	s_add_u32 s18, s18, 0x40000
	s_addc_u32 s19, s19, 0
	s_mov_b32 m0, s27
	v_lshl_add_u64 v[214:215], s[18:19], 0, v[158:159]
	ds_read_b128 v[182:185], v199 offset:32768
	ds_read_b128 v[186:189], v199 offset:33792
	ds_read_b128 v[200:203], v199 offset:34816
	ds_read_b128 v[204:207], v199 offset:35840
	ds_read_b128 v[220:223], v199 offset:36864
	ds_read_b128 v[224:227], v199 offset:37888
	ds_read_b128 v[228:231], v199 offset:38912
	ds_read_b128 v[232:235], v199 offset:39936
	global_load_lds_dwordx4 v[214:215], off
	v_lshl_add_u64 v[214:215], s[18:19], 0, v[156:157]
	s_mov_b32 m0, s28
	s_nop 0
	global_load_lds_dwordx4 v[214:215], off
	s_waitcnt vmcnt(8)
	s_waitcnt lgkmcnt(0)
	s_barrier
	s_setprio 1
	s_waitcnt lgkmcnt(0)
	v_mfma_f32_16x16x32_bf16 v[126:129], v[130:133], v[182:185], v[126:129]
	v_mfma_f32_16x16x32_bf16 v[118:121], v[138:141], v[182:185], v[118:121]
	v_mfma_f32_16x16x32_bf16 v[102:105], v[138:141], v[200:203], v[102:105]
	v_mfma_f32_16x16x32_bf16 v[110:113], v[130:133], v[200:203], v[110:113]
	v_mfma_f32_16x16x32_bf16 v[94:97], v[130:133], v[220:223], v[94:97]
	v_mfma_f32_16x16x32_bf16 v[86:89], v[138:141], v[220:223], v[86:89]
	v_mfma_f32_16x16x32_bf16 v[70:73], v[138:141], v[228:231], v[70:73]
	v_mfma_f32_16x16x32_bf16 v[78:81], v[130:133], v[228:231], v[78:81]
	v_mfma_f32_16x16x32_bf16 v[126:129], v[134:137], v[186:189], v[126:129]
	v_mfma_f32_16x16x32_bf16 v[118:121], v[142:145], v[186:189], v[118:121]
	v_mfma_f32_16x16x32_bf16 v[102:105], v[142:145], v[204:207], v[102:105]
	v_mfma_f32_16x16x32_bf16 v[110:113], v[134:137], v[204:207], v[110:113]
	v_mfma_f32_16x16x32_bf16 v[94:97], v[134:137], v[224:227], v[94:97]
	v_mfma_f32_16x16x32_bf16 v[86:89], v[142:145], v[224:227], v[86:89]
	v_mfma_f32_16x16x32_bf16 v[70:73], v[142:145], v[232:235], v[70:73]
	v_mfma_f32_16x16x32_bf16 v[78:81], v[134:137], v[232:235], v[78:81]
	s_setprio 0
	s_setprio 1
	v_mfma_f32_16x16x32_bf16 v[122:125], v[146:149], v[182:185], v[122:125]
	v_mfma_f32_16x16x32_bf16 v[114:117], v[174:177], v[182:185], v[114:117]
	v_mfma_f32_16x16x32_bf16 v[98:101], v[174:177], v[200:203], v[98:101]
	v_mfma_f32_16x16x32_bf16 v[106:109], v[146:149], v[200:203], v[106:109]
	v_mfma_f32_16x16x32_bf16 v[90:93], v[146:149], v[220:223], v[90:93]
	v_mfma_f32_16x16x32_bf16 v[82:85], v[174:177], v[220:223], v[82:85]
	v_mfma_f32_16x16x32_bf16 v[66:69], v[174:177], v[228:231], v[66:69]
	v_mfma_f32_16x16x32_bf16 v[74:77], v[146:149], v[228:231], v[74:77]
	v_mfma_f32_16x16x32_bf16 v[122:125], v[150:153], v[186:189], v[122:125]
	v_mfma_f32_16x16x32_bf16 v[114:117], v[178:181], v[186:189], v[114:117]
	v_mfma_f32_16x16x32_bf16 v[98:101], v[178:181], v[204:207], v[98:101]
	v_mfma_f32_16x16x32_bf16 v[106:109], v[150:153], v[204:207], v[106:109]
	v_mfma_f32_16x16x32_bf16 v[90:93], v[150:153], v[224:227], v[90:93]
	v_mfma_f32_16x16x32_bf16 v[82:85], v[178:181], v[224:227], v[82:85]
	v_mfma_f32_16x16x32_bf16 v[66:69], v[178:181], v[232:235], v[66:69]
	v_mfma_f32_16x16x32_bf16 v[74:77], v[150:153], v[232:235], v[74:77]
	s_setprio 0
	s_barrier
	s_add_i32 s18, s42, s22
	v_lshl_add_u64 v[162:163], v[162:163], 0, s[86:87]
	s_mov_b32 m0, s18
	ds_read_b128 v[182:185], v199 offset:49152
	ds_read_b128 v[186:189], v199 offset:50176
	ds_read_b128 v[200:203], v199 offset:51200
	ds_read_b128 v[204:207], v199 offset:52224
	ds_read_b128 v[220:223], v199 offset:53248
	ds_read_b128 v[224:227], v199 offset:54272
	ds_read_b128 v[228:231], v199 offset:55296
	ds_read_b128 v[232:235], v199 offset:56320
	global_load_lds_dwordx4 v[162:163], off
	s_add_i32 m0, s18, 0x2000
	s_add_u32 s16, s16, 0x40080
	v_lshl_add_u64 v[162:163], v[190:191], 0, s[86:87]
	s_addc_u32 s17, s17, 0
	s_add_i32 s18, s43, s22
	global_load_lds_dwordx4 v[162:163], off
	v_lshl_add_u64 v[162:163], s[16:17], 0, v[0:1]
	s_mov_b32 m0, s18
	s_nop 0
	global_load_lds_dwordx4 v[162:163], off
	v_lshl_add_u64 v[162:163], s[16:17], 0, v[154:155]
	s_add_i32 m0, s18, 0x2000
	s_nop 0
	global_load_lds_dwordx4 v[162:163], off
	v_lshl_add_u64 v[162:163], v[196:197], 0, s[86:87]
	s_mov_b32 m0, s29
	s_nop 0
	global_load_lds_dwordx4 v[162:163], off
	v_lshl_add_u64 v[162:163], v[208:209], 0, s[86:87]
	s_mov_b32 m0, s30
	s_nop 0
	global_load_lds_dwordx4 v[162:163], off
	s_waitcnt vmcnt(8)
	s_waitcnt lgkmcnt(0)
	s_barrier
	s_setprio 1
	s_waitcnt lgkmcnt(0)
	v_mfma_f32_16x16x32_bf16 v[62:65], v[130:133], v[182:185], v[62:65]
	v_mfma_f32_16x16x32_bf16 v[54:57], v[138:141], v[182:185], v[54:57]
	v_mfma_f32_16x16x32_bf16 v[38:41], v[138:141], v[200:203], v[38:41]
	v_mfma_f32_16x16x32_bf16 v[46:49], v[130:133], v[200:203], v[46:49]
	v_mfma_f32_16x16x32_bf16 v[30:33], v[130:133], v[220:223], v[30:33]
	v_mfma_f32_16x16x32_bf16 v[22:25], v[138:141], v[220:223], v[22:25]
	v_mfma_f32_16x16x32_bf16 v[6:9], v[138:141], v[228:231], v[6:9]
	v_mfma_f32_16x16x32_bf16 v[14:17], v[130:133], v[228:231], v[14:17]
	v_mfma_f32_16x16x32_bf16 v[62:65], v[134:137], v[186:189], v[62:65]
	v_mfma_f32_16x16x32_bf16 v[54:57], v[142:145], v[186:189], v[54:57]
	v_mfma_f32_16x16x32_bf16 v[38:41], v[142:145], v[204:207], v[38:41]
	v_mfma_f32_16x16x32_bf16 v[46:49], v[134:137], v[204:207], v[46:49]
	v_mfma_f32_16x16x32_bf16 v[30:33], v[134:137], v[224:227], v[30:33]
	v_mfma_f32_16x16x32_bf16 v[22:25], v[142:145], v[224:227], v[22:25]
	v_mfma_f32_16x16x32_bf16 v[6:9], v[142:145], v[232:235], v[6:9]
	v_mfma_f32_16x16x32_bf16 v[14:17], v[134:137], v[232:235], v[14:17]
	s_setprio 0
	s_setprio 1
	v_mfma_f32_16x16x32_bf16 v[58:61], v[146:149], v[182:185], v[58:61]
	v_mfma_f32_16x16x32_bf16 v[50:53], v[174:177], v[182:185], v[50:53]
	v_mfma_f32_16x16x32_bf16 v[34:37], v[174:177], v[200:203], v[34:37]
	v_mfma_f32_16x16x32_bf16 v[42:45], v[146:149], v[200:203], v[42:45]
	v_mfma_f32_16x16x32_bf16 v[26:29], v[146:149], v[220:223], v[26:29]
	v_mfma_f32_16x16x32_bf16 v[18:21], v[174:177], v[220:223], v[18:21]
	v_mfma_f32_16x16x32_bf16 v[2:5], v[174:177], v[228:231], v[2:5]
	v_mfma_f32_16x16x32_bf16 v[10:13], v[146:149], v[228:231], v[10:13]
	v_mfma_f32_16x16x32_bf16 v[58:61], v[150:153], v[186:189], v[58:61]
	v_mfma_f32_16x16x32_bf16 v[50:53], v[178:181], v[186:189], v[50:53]
	v_mfma_f32_16x16x32_bf16 v[34:37], v[178:181], v[204:207], v[34:37]
	v_mfma_f32_16x16x32_bf16 v[42:45], v[150:153], v[204:207], v[42:45]
	v_mfma_f32_16x16x32_bf16 v[26:29], v[150:153], v[224:227], v[26:29]
	v_mfma_f32_16x16x32_bf16 v[18:21], v[178:181], v[224:227], v[18:21]
	v_mfma_f32_16x16x32_bf16 v[2:5], v[178:181], v[232:235], v[2:5]
	v_mfma_f32_16x16x32_bf16 v[10:13], v[150:153], v[232:235], v[10:13]
	s_setprio 0
	s_barrier
	s_add_i32 s41, s41, 2
	s_add_u32 s4, s4, 0x100
	s_addc_u32 s5, s5, 0
	s_add_u32 s39, s39, 0x100
	s_addc_u32 s40, s40, 0
	s_cmp_gt_u32 s41, 13
	s_cbranch_scc0 .LBB0_1446
.LBB0_1446:
	s_add_u32 s16, s4, 0xfffc0080
	s_addc_u32 s17, s5, -1
	s_add_i32 s42, 0, 0x10000
	s_cmp_eq_u32 s41, 12
	s_cselect_b32 s19, s11, s17
	s_cselect_b32 s18, s37, s16
	s_cselect_b32 s17, s9, s40
	s_cselect_b32 s16, s38, s39
	s_add_i32 s44, 0, 0x14000
	v_add_u32_e32 v142, s42, v195
	v_add_u32_e32 v162, s44, v195
	ds_read_b128 v[130:133], v142
	ds_read_b128 v[134:137], v142 offset:1024
	ds_read_b128 v[138:141], v142 offset:2048
	ds_read_b128 v[142:145], v142 offset:3072
	ds_read_b128 v[146:149], v162
	ds_read_b128 v[150:153], v162 offset:1024
	ds_read_b128 v[174:177], v162 offset:2048
	ds_read_b128 v[178:181], v162 offset:3072
	v_lshl_add_u64 v[162:163], s[4:5], 0, v[170:171]
	s_add_i32 m0, s23, 0xc000
	ds_read_b128 v[182:185], v199
	ds_read_b128 v[186:189], v199 offset:1024
	ds_read_b128 v[200:203], v199 offset:2048
	ds_read_b128 v[204:207], v199 offset:3072
	ds_read_b128 v[220:223], v199 offset:4096
	ds_read_b128 v[224:227], v199 offset:5120
	ds_read_b128 v[228:231], v199 offset:6144
	ds_read_b128 v[232:235], v199 offset:7168
	global_load_lds_dwordx4 v[162:163], off
	v_lshl_add_u64 v[162:163], s[4:5], 0, v[172:173]
	s_add_i32 m0, s23, 0xe000
	s_nop 0
	global_load_lds_dwordx4 v[162:163], off
	s_waitcnt vmcnt(8)
	s_waitcnt lgkmcnt(0)
	s_barrier
	s_setprio 1
	s_waitcnt lgkmcnt(0)
	v_mfma_f32_16x16x32_bf16 v[126:129], v[130:133], v[182:185], v[126:129]
	v_mfma_f32_16x16x32_bf16 v[118:121], v[138:141], v[182:185], v[118:121]
	v_mfma_f32_16x16x32_bf16 v[102:105], v[138:141], v[200:203], v[102:105]
	v_mfma_f32_16x16x32_bf16 v[110:113], v[130:133], v[200:203], v[110:113]
	v_mfma_f32_16x16x32_bf16 v[94:97], v[130:133], v[220:223], v[94:97]
	v_mfma_f32_16x16x32_bf16 v[86:89], v[138:141], v[220:223], v[86:89]
	v_mfma_f32_16x16x32_bf16 v[70:73], v[138:141], v[228:231], v[70:73]
	v_mfma_f32_16x16x32_bf16 v[78:81], v[130:133], v[228:231], v[78:81]
	v_mfma_f32_16x16x32_bf16 v[126:129], v[134:137], v[186:189], v[126:129]
	v_mfma_f32_16x16x32_bf16 v[118:121], v[142:145], v[186:189], v[118:121]
	v_mfma_f32_16x16x32_bf16 v[102:105], v[142:145], v[204:207], v[102:105]
	v_mfma_f32_16x16x32_bf16 v[110:113], v[134:137], v[204:207], v[110:113]
	v_mfma_f32_16x16x32_bf16 v[94:97], v[134:137], v[224:227], v[94:97]
	v_mfma_f32_16x16x32_bf16 v[86:89], v[142:145], v[224:227], v[86:89]
	v_mfma_f32_16x16x32_bf16 v[70:73], v[142:145], v[232:235], v[70:73]
	v_mfma_f32_16x16x32_bf16 v[78:81], v[134:137], v[232:235], v[78:81]
	s_setprio 0
	s_setprio 1
	v_mfma_f32_16x16x32_bf16 v[122:125], v[146:149], v[182:185], v[122:125]
	v_mfma_f32_16x16x32_bf16 v[114:117], v[174:177], v[182:185], v[114:117]
	v_mfma_f32_16x16x32_bf16 v[98:101], v[174:177], v[200:203], v[98:101]
	v_mfma_f32_16x16x32_bf16 v[106:109], v[146:149], v[200:203], v[106:109]
	v_mfma_f32_16x16x32_bf16 v[90:93], v[146:149], v[220:223], v[90:93]
	v_mfma_f32_16x16x32_bf16 v[82:85], v[174:177], v[220:223], v[82:85]
	v_mfma_f32_16x16x32_bf16 v[66:69], v[174:177], v[228:231], v[66:69]
	v_mfma_f32_16x16x32_bf16 v[74:77], v[146:149], v[228:231], v[74:77]
	v_mfma_f32_16x16x32_bf16 v[122:125], v[150:153], v[186:189], v[122:125]
	v_mfma_f32_16x16x32_bf16 v[114:117], v[178:181], v[186:189], v[114:117]
	v_mfma_f32_16x16x32_bf16 v[98:101], v[178:181], v[204:207], v[98:101]
	v_mfma_f32_16x16x32_bf16 v[106:109], v[150:153], v[204:207], v[106:109]
	v_mfma_f32_16x16x32_bf16 v[90:93], v[150:153], v[224:227], v[90:93]
	v_mfma_f32_16x16x32_bf16 v[82:85], v[178:181], v[224:227], v[82:85]
	v_mfma_f32_16x16x32_bf16 v[66:69], v[178:181], v[232:235], v[66:69]
	v_mfma_f32_16x16x32_bf16 v[74:77], v[150:153], v[232:235], v[74:77]
	s_setprio 0
	s_barrier
	s_add_i32 s42, s42, s22
	v_lshl_add_u64 v[162:163], s[16:17], 0, v[0:1]
	s_mov_b32 m0, s42
	ds_read_b128 v[182:185], v199 offset:16384
	ds_read_b128 v[186:189], v199 offset:17408
	ds_read_b128 v[200:203], v199 offset:18432
	ds_read_b128 v[204:207], v199 offset:19456
	ds_read_b128 v[220:223], v199 offset:20480
	ds_read_b128 v[224:227], v199 offset:21504
	ds_read_b128 v[228:231], v199 offset:22528
	ds_read_b128 v[232:235], v199 offset:23552
	global_load_lds_dwordx4 v[162:163], off
	s_add_i32 m0, s42, 0x2000
	s_add_u32 s42, s16, 0x40000
	v_lshl_add_u64 v[190:191], s[16:17], 0, v[154:155]
	s_addc_u32 s43, s17, 0
	s_add_i32 s44, s44, s22
	global_load_lds_dwordx4 v[190:191], off
	v_lshl_add_u64 v[196:197], s[42:43], 0, v[0:1]
	s_mov_b32 m0, s44
	v_lshl_add_u64 v[208:209], s[18:19], 0, v[156:157]
	global_load_lds_dwordx4 v[196:197], off
	v_lshl_add_u64 v[196:197], s[42:43], 0, v[154:155]
	s_add_i32 m0, s44, 0x2000
	s_nop 0
	global_load_lds_dwordx4 v[196:197], off
	v_lshl_add_u64 v[196:197], s[18:19], 0, v[158:159]
	s_mov_b32 m0, s23
	s_nop 0
	global_load_lds_dwordx4 v[196:197], off
	s_mov_b32 m0, s26
	s_nop 0
	global_load_lds_dwordx4 v[208:209], off
	s_waitcnt vmcnt(8)
	s_waitcnt lgkmcnt(0)
	s_barrier
	s_setprio 1
	s_waitcnt lgkmcnt(0)
	v_mfma_f32_16x16x32_bf16 v[62:65], v[130:133], v[182:185], v[62:65]
	v_mfma_f32_16x16x32_bf16 v[54:57], v[138:141], v[182:185], v[54:57]
	v_mfma_f32_16x16x32_bf16 v[38:41], v[138:141], v[200:203], v[38:41]
	v_mfma_f32_16x16x32_bf16 v[46:49], v[130:133], v[200:203], v[46:49]
	v_mfma_f32_16x16x32_bf16 v[30:33], v[130:133], v[220:223], v[30:33]
	v_mfma_f32_16x16x32_bf16 v[22:25], v[138:141], v[220:223], v[22:25]
	v_mfma_f32_16x16x32_bf16 v[6:9], v[138:141], v[228:231], v[6:9]
	v_mfma_f32_16x16x32_bf16 v[14:17], v[130:133], v[228:231], v[14:17]
	v_mfma_f32_16x16x32_bf16 v[62:65], v[134:137], v[186:189], v[62:65]
	v_mfma_f32_16x16x32_bf16 v[54:57], v[142:145], v[186:189], v[54:57]
	v_mfma_f32_16x16x32_bf16 v[38:41], v[142:145], v[204:207], v[38:41]
	v_mfma_f32_16x16x32_bf16 v[46:49], v[134:137], v[204:207], v[46:49]
	v_mfma_f32_16x16x32_bf16 v[30:33], v[134:137], v[224:227], v[30:33]
	v_mfma_f32_16x16x32_bf16 v[22:25], v[142:145], v[224:227], v[22:25]
	v_mfma_f32_16x16x32_bf16 v[6:9], v[142:145], v[232:235], v[6:9]
	v_mfma_f32_16x16x32_bf16 v[14:17], v[134:137], v[232:235], v[14:17]
	s_setprio 0
	s_setprio 1
	v_mfma_f32_16x16x32_bf16 v[58:61], v[146:149], v[182:185], v[58:61]
	v_mfma_f32_16x16x32_bf16 v[50:53], v[174:177], v[182:185], v[50:53]
	v_mfma_f32_16x16x32_bf16 v[34:37], v[174:177], v[200:203], v[34:37]
	v_mfma_f32_16x16x32_bf16 v[42:45], v[146:149], v[200:203], v[42:45]
	v_mfma_f32_16x16x32_bf16 v[26:29], v[146:149], v[220:223], v[26:29]
	v_mfma_f32_16x16x32_bf16 v[18:21], v[174:177], v[220:223], v[18:21]
	v_mfma_f32_16x16x32_bf16 v[2:5], v[174:177], v[228:231], v[2:5]
	v_mfma_f32_16x16x32_bf16 v[10:13], v[146:149], v[228:231], v[10:13]
	v_mfma_f32_16x16x32_bf16 v[58:61], v[150:153], v[186:189], v[58:61]
	v_mfma_f32_16x16x32_bf16 v[50:53], v[178:181], v[186:189], v[50:53]
	v_mfma_f32_16x16x32_bf16 v[34:37], v[178:181], v[204:207], v[34:37]
	v_mfma_f32_16x16x32_bf16 v[42:45], v[150:153], v[204:207], v[42:45]
	v_mfma_f32_16x16x32_bf16 v[26:29], v[150:153], v[224:227], v[26:29]
	v_mfma_f32_16x16x32_bf16 v[18:21], v[178:181], v[224:227], v[18:21]
	v_mfma_f32_16x16x32_bf16 v[2:5], v[178:181], v[232:235], v[2:5]
	v_mfma_f32_16x16x32_bf16 v[10:13], v[150:153], v[232:235], v[10:13]
	s_setprio 0
	s_barrier
	s_add_i32 s42, 0, 0x18000
	s_add_i32 s43, 0, 0x1c000
	v_add_u32_e32 v142, s42, v195
	v_add_u32_e32 v164, s43, v195
	ds_read_b128 v[130:133], v142
	ds_read_b128 v[134:137], v142 offset:1024
	ds_read_b128 v[138:141], v142 offset:2048
	ds_read_b128 v[142:145], v142 offset:3072
	ds_read_b128 v[146:149], v164
	ds_read_b128 v[150:153], v164 offset:1024
	ds_read_b128 v[174:177], v164 offset:2048
	ds_read_b128 v[178:181], v164 offset:3072
	s_add_u32 s18, s18, 0x40000
	s_addc_u32 s19, s19, 0
	s_mov_b32 m0, s27
	v_lshl_add_u64 v[214:215], s[18:19], 0, v[158:159]
	ds_read_b128 v[182:185], v199 offset:32768
	ds_read_b128 v[186:189], v199 offset:33792
	ds_read_b128 v[200:203], v199 offset:34816
	ds_read_b128 v[204:207], v199 offset:35840
	ds_read_b128 v[220:223], v199 offset:36864
	ds_read_b128 v[224:227], v199 offset:37888
	ds_read_b128 v[228:231], v199 offset:38912
	ds_read_b128 v[232:235], v199 offset:39936
	global_load_lds_dwordx4 v[214:215], off
	v_lshl_add_u64 v[214:215], s[18:19], 0, v[156:157]
	s_mov_b32 m0, s28
	s_nop 0
	global_load_lds_dwordx4 v[214:215], off
	s_waitcnt vmcnt(8)
	s_waitcnt lgkmcnt(0)
	s_barrier
	s_setprio 1
	s_waitcnt lgkmcnt(0)
	v_mfma_f32_16x16x32_bf16 v[126:129], v[130:133], v[182:185], v[126:129]
	v_mfma_f32_16x16x32_bf16 v[118:121], v[138:141], v[182:185], v[118:121]
	v_mfma_f32_16x16x32_bf16 v[102:105], v[138:141], v[200:203], v[102:105]
	v_mfma_f32_16x16x32_bf16 v[110:113], v[130:133], v[200:203], v[110:113]
	v_mfma_f32_16x16x32_bf16 v[94:97], v[130:133], v[220:223], v[94:97]
	v_mfma_f32_16x16x32_bf16 v[86:89], v[138:141], v[220:223], v[86:89]
	v_mfma_f32_16x16x32_bf16 v[70:73], v[138:141], v[228:231], v[70:73]
	v_mfma_f32_16x16x32_bf16 v[78:81], v[130:133], v[228:231], v[78:81]
	v_mfma_f32_16x16x32_bf16 v[126:129], v[134:137], v[186:189], v[126:129]
	v_mfma_f32_16x16x32_bf16 v[118:121], v[142:145], v[186:189], v[118:121]
	v_mfma_f32_16x16x32_bf16 v[102:105], v[142:145], v[204:207], v[102:105]
	v_mfma_f32_16x16x32_bf16 v[110:113], v[134:137], v[204:207], v[110:113]
	v_mfma_f32_16x16x32_bf16 v[94:97], v[134:137], v[224:227], v[94:97]
	v_mfma_f32_16x16x32_bf16 v[86:89], v[142:145], v[224:227], v[86:89]
	v_mfma_f32_16x16x32_bf16 v[70:73], v[142:145], v[232:235], v[70:73]
	v_mfma_f32_16x16x32_bf16 v[78:81], v[134:137], v[232:235], v[78:81]
	s_setprio 0
	s_setprio 1
	v_mfma_f32_16x16x32_bf16 v[122:125], v[146:149], v[182:185], v[122:125]
	v_mfma_f32_16x16x32_bf16 v[114:117], v[174:177], v[182:185], v[114:117]
	v_mfma_f32_16x16x32_bf16 v[98:101], v[174:177], v[200:203], v[98:101]
	v_mfma_f32_16x16x32_bf16 v[106:109], v[146:149], v[200:203], v[106:109]
	v_mfma_f32_16x16x32_bf16 v[90:93], v[146:149], v[220:223], v[90:93]
	v_mfma_f32_16x16x32_bf16 v[82:85], v[174:177], v[220:223], v[82:85]
	v_mfma_f32_16x16x32_bf16 v[66:69], v[174:177], v[228:231], v[66:69]
	v_mfma_f32_16x16x32_bf16 v[74:77], v[146:149], v[228:231], v[74:77]
	v_mfma_f32_16x16x32_bf16 v[122:125], v[150:153], v[186:189], v[122:125]
	v_mfma_f32_16x16x32_bf16 v[114:117], v[178:181], v[186:189], v[114:117]
	v_mfma_f32_16x16x32_bf16 v[98:101], v[178:181], v[204:207], v[98:101]
	v_mfma_f32_16x16x32_bf16 v[106:109], v[150:153], v[204:207], v[106:109]
	v_mfma_f32_16x16x32_bf16 v[90:93], v[150:153], v[224:227], v[90:93]
	v_mfma_f32_16x16x32_bf16 v[82:85], v[178:181], v[224:227], v[82:85]
	v_mfma_f32_16x16x32_bf16 v[66:69], v[178:181], v[232:235], v[66:69]
	v_mfma_f32_16x16x32_bf16 v[74:77], v[150:153], v[232:235], v[74:77]
	s_setprio 0
	s_barrier
	s_add_i32 s18, s42, s22
	v_lshl_add_u64 v[162:163], v[162:163], 0, s[86:87]
	s_mov_b32 m0, s18
	ds_read_b128 v[182:185], v199 offset:49152
	ds_read_b128 v[186:189], v199 offset:50176
	ds_read_b128 v[200:203], v199 offset:51200
	ds_read_b128 v[204:207], v199 offset:52224
	ds_read_b128 v[220:223], v199 offset:53248
	ds_read_b128 v[224:227], v199 offset:54272
	ds_read_b128 v[228:231], v199 offset:55296
	ds_read_b128 v[232:235], v199 offset:56320
	global_load_lds_dwordx4 v[162:163], off
	s_add_i32 m0, s18, 0x2000
	s_add_u32 s16, s16, 0x40080
	v_lshl_add_u64 v[162:163], v[190:191], 0, s[86:87]
	s_addc_u32 s17, s17, 0
	s_add_i32 s18, s43, s22
	global_load_lds_dwordx4 v[162:163], off
	v_lshl_add_u64 v[162:163], s[16:17], 0, v[0:1]
	s_mov_b32 m0, s18
	s_nop 0
	global_load_lds_dwordx4 v[162:163], off
	v_lshl_add_u64 v[162:163], s[16:17], 0, v[154:155]
	s_add_i32 m0, s18, 0x2000
	s_nop 0
	global_load_lds_dwordx4 v[162:163], off
	v_lshl_add_u64 v[162:163], v[196:197], 0, s[86:87]
	s_mov_b32 m0, s29
	s_nop 0
	global_load_lds_dwordx4 v[162:163], off
	v_lshl_add_u64 v[162:163], v[208:209], 0, s[86:87]
	s_mov_b32 m0, s30
	s_nop 0
	global_load_lds_dwordx4 v[162:163], off
	s_waitcnt vmcnt(8)
	s_waitcnt lgkmcnt(0)
	s_barrier
	s_setprio 1
	s_waitcnt lgkmcnt(0)
	v_mfma_f32_16x16x32_bf16 v[62:65], v[130:133], v[182:185], v[62:65]
	v_mfma_f32_16x16x32_bf16 v[54:57], v[138:141], v[182:185], v[54:57]
	v_mfma_f32_16x16x32_bf16 v[38:41], v[138:141], v[200:203], v[38:41]
	v_mfma_f32_16x16x32_bf16 v[46:49], v[130:133], v[200:203], v[46:49]
	v_mfma_f32_16x16x32_bf16 v[30:33], v[130:133], v[220:223], v[30:33]
	v_mfma_f32_16x16x32_bf16 v[22:25], v[138:141], v[220:223], v[22:25]
	v_mfma_f32_16x16x32_bf16 v[6:9], v[138:141], v[228:231], v[6:9]
	v_mfma_f32_16x16x32_bf16 v[14:17], v[130:133], v[228:231], v[14:17]
	v_mfma_f32_16x16x32_bf16 v[62:65], v[134:137], v[186:189], v[62:65]
	v_mfma_f32_16x16x32_bf16 v[54:57], v[142:145], v[186:189], v[54:57]
	v_mfma_f32_16x16x32_bf16 v[38:41], v[142:145], v[204:207], v[38:41]
	v_mfma_f32_16x16x32_bf16 v[46:49], v[134:137], v[204:207], v[46:49]
	v_mfma_f32_16x16x32_bf16 v[30:33], v[134:137], v[224:227], v[30:33]
	v_mfma_f32_16x16x32_bf16 v[22:25], v[142:145], v[224:227], v[22:25]
	v_mfma_f32_16x16x32_bf16 v[6:9], v[142:145], v[232:235], v[6:9]
	v_mfma_f32_16x16x32_bf16 v[14:17], v[134:137], v[232:235], v[14:17]
	s_setprio 0
	s_setprio 1
	v_mfma_f32_16x16x32_bf16 v[58:61], v[146:149], v[182:185], v[58:61]
	v_mfma_f32_16x16x32_bf16 v[50:53], v[174:177], v[182:185], v[50:53]
	v_mfma_f32_16x16x32_bf16 v[34:37], v[174:177], v[200:203], v[34:37]
	v_mfma_f32_16x16x32_bf16 v[42:45], v[146:149], v[200:203], v[42:45]
	v_mfma_f32_16x16x32_bf16 v[26:29], v[146:149], v[220:223], v[26:29]
	v_mfma_f32_16x16x32_bf16 v[18:21], v[174:177], v[220:223], v[18:21]
	v_mfma_f32_16x16x32_bf16 v[2:5], v[174:177], v[228:231], v[2:5]
	v_mfma_f32_16x16x32_bf16 v[10:13], v[146:149], v[228:231], v[10:13]
	v_mfma_f32_16x16x32_bf16 v[58:61], v[150:153], v[186:189], v[58:61]
	v_mfma_f32_16x16x32_bf16 v[50:53], v[178:181], v[186:189], v[50:53]
	v_mfma_f32_16x16x32_bf16 v[34:37], v[178:181], v[204:207], v[34:37]
	v_mfma_f32_16x16x32_bf16 v[42:45], v[150:153], v[204:207], v[42:45]
	v_mfma_f32_16x16x32_bf16 v[26:29], v[150:153], v[224:227], v[26:29]
	v_mfma_f32_16x16x32_bf16 v[18:21], v[178:181], v[224:227], v[18:21]
	v_mfma_f32_16x16x32_bf16 v[2:5], v[178:181], v[232:235], v[2:5]
	v_mfma_f32_16x16x32_bf16 v[10:13], v[150:153], v[232:235], v[10:13]
	s_setprio 0
	s_barrier
	s_add_i32 s41, s41, 2
	s_add_u32 s4, s4, 0x100
	s_addc_u32 s5, s5, 0
	s_add_u32 s39, s39, 0x100
	s_addc_u32 s40, s40, 0
	s_cmp_gt_u32 s41, 13
	s_cbranch_scc0 .LBB0_1446
